# hand-written S5 carry scan with wide accesses (lane = 4 states, dwordx2 loads/stores, packed F in registers)
# baseline (speedup 1.0000x reference)
; __device__ __forceinline__ float bf2f(bf16_t v) { return __uint_as_float((unsigned)v << 16); }
; #define LAS __attribute__((address_space(3)))
; __device__ __forceinline__ void s5_scan_bg(LAS unsigned char* lds, const S5In P, const bf16_t* F, bf16_t* XB, int b, int g, const int tid) {
;     const int lane = tid & 63, wid = __builtin_amdgcn_readfirstlane(tid >> 6), p = lane;
;     LAS f32x2v* E = (LAS f32x2v*)lds;
;     LAS f32x2v* XI = (LAS f32x2v*)(lds + 16384);
;     float a1r[2], a1i[2], a16r[2], a16i[2];
; #pragma unroll
;     for (int di = 0; di < 2; ++di) { const int gp = (di * 64 + g) * 64 + p;
;         const float dt = expf(P.log_dt[di * 64 + g]); const float lr = P.lam_re[gp], li = P.lam_im[gp];
;         const float mag = expf(lr * dt), ang = li * dt; float ar = mag * cosf(ang), ai = mag * sinf(ang);
; #pragma unroll
;         for (int sq = 0; sq < 4; ++sq) { const float t = ar * ar - ai * ai; ai = 2.f * ar * ai; ar = t; }
;         a1r[di] = ar; a1i[di] = ai;
; #pragma unroll
;         for (int sq = 0; sq < 4; ++sq) { const float t = ar * ar - ai * ai; ai = 2.f * ar * ai; ar = t; }
;         a16r[di] = ar; a16i[di] = ai; }
;     const bf16_t* Fb = F + ((size_t)g * 1024 + b * 256) * 256;
;     float fr[4][16], fi[4][16];
; #pragma unroll
;     for (int jj = 0; jj < 4; ++jj) { const int job = wid + 8 * jj, di = job >> 4, seg = job & 15;
; #pragma unroll
;         for (int j = 0; j < 16; ++j) { const int c = di == 0 ? seg * 16 + j : 255 - (seg * 16 + j); const bf16_t* fp = Fb + (size_t)c * 256 + di * 128 + p; fr[jj][j] = bf2f(fp[0]); fi[jj][j] = bf2f(fp[64]); } }
.LBB0_792:
	v_readlane_b32 s4, v254, 33
	v_readlane_b32 s5, v254, 34
	v_readlane_b32 s6, v252, 63
	ds_read_b64 v[160:161], v236 offset:56
	ds_read_b64 v[162:163], v236 offset:64
	ds_read_b64 v[164:165], v236 offset:72
	v_readfirstlane_b32 s26, v147
	s_waitcnt lgkmcnt(0)
	v_readfirstlane_b32 s8, v160
	v_readfirstlane_b32 s9, v161
	v_readfirstlane_b32 s10, v162
	v_readfirstlane_b32 s11, v163
	v_readfirstlane_b32 s12, v164
	v_readfirstlane_b32 s13, v165
	s_nop 3
	s_lshr_b32 s26, s26, 6
	s_lshr_b32 s27, s26, 2
	s_and_b32 s14, s6, 7
	s_lshl_b32 s14, s14, 5
	s_lshr_b32 s15, s6, 3
	s_add_i32 s14, s14, s15
	s_and_b32 s15, s14, 3
	s_lshr_b32 s16, s14, 2
	s_lshl_b32 s17, s16, 19
	s_lshl_b32 s18, s15, 17
	s_add_u32 s17, s17, s18
	s_add_u32 s20, s4, 0x7600000
	s_addc_u32 s21, s5, 0
	s_add_u32 s20, s20, s17
	s_addc_u32 s21, s21, 0
	s_add_u32 s24, s4, 0xb600000
	s_addc_u32 s25, s5, 0
	s_add_u32 s24, s24, s17
	s_addc_u32 s25, s25, 0
	v_and_b32_e32 v160, 63, v147
	v_lshrrev_b32_e32 v161, 4, v160
	v_and_b32_e32 v162, 15, v160
	s_lshl_b32 s28, s26, 2
	v_add_u32_e32 v163, s28, v161
	v_and_b32_e32 v164, 15, v163
	v_lshlrev_b32_e32 v165, 4, v164
	s_cmp_eq_u32 s27, 0
	s_cselect_b64 vcc, -1, 0
	v_sub_u32_e32 v166, 0xf0, v165
	v_cndmask_b32_e32 v165, v166, v165, vcc
	v_lshlrev_b32_e32 v100, 9, v165
	v_lshl_add_u32 v100, v162, 3, v100
	s_lshl_b32 s28, s27, 8
	v_add_u32_e32 v100, s28, v100
	v_add_u32_e32 v101, 0x1000, v100
	s_cmp_eq_u32 s27, 0
	s_cbranch_scc0 .Lscan2_ld1
	global_load_dwordx2 v[0:1], v100, s[20:21]
	global_load_dwordx2 v[2:3], v100, s[20:21] offset:128
	global_load_dwordx2 v[4:5], v100, s[20:21] offset:512
	global_load_dwordx2 v[6:7], v100, s[20:21] offset:640
	global_load_dwordx2 v[8:9], v100, s[20:21] offset:1024
	global_load_dwordx2 v[10:11], v100, s[20:21] offset:1152
	global_load_dwordx2 v[12:13], v100, s[20:21] offset:1536
	global_load_dwordx2 v[14:15], v100, s[20:21] offset:1664
	global_load_dwordx2 v[16:17], v100, s[20:21] offset:2048
	global_load_dwordx2 v[18:19], v100, s[20:21] offset:2176
	global_load_dwordx2 v[20:21], v100, s[20:21] offset:2560
	global_load_dwordx2 v[22:23], v100, s[20:21] offset:2688
	global_load_dwordx2 v[24:25], v100, s[20:21] offset:3072
	global_load_dwordx2 v[26:27], v100, s[20:21] offset:3200
	global_load_dwordx2 v[28:29], v100, s[20:21] offset:3584
	global_load_dwordx2 v[30:31], v100, s[20:21] offset:3712
	global_load_dwordx2 v[32:33], v101, s[20:21]
	global_load_dwordx2 v[34:35], v101, s[20:21] offset:128
	global_load_dwordx2 v[36:37], v101, s[20:21] offset:512
	global_load_dwordx2 v[38:39], v101, s[20:21] offset:640
	global_load_dwordx2 v[40:41], v101, s[20:21] offset:1024
	global_load_dwordx2 v[42:43], v101, s[20:21] offset:1152
	global_load_dwordx2 v[44:45], v101, s[20:21] offset:1536
	global_load_dwordx2 v[46:47], v101, s[20:21] offset:1664
	global_load_dwordx2 v[48:49], v101, s[20:21] offset:2048
	global_load_dwordx2 v[50:51], v101, s[20:21] offset:2176
	global_load_dwordx2 v[52:53], v101, s[20:21] offset:2560
	global_load_dwordx2 v[54:55], v101, s[20:21] offset:2688
	global_load_dwordx2 v[56:57], v101, s[20:21] offset:3072
	global_load_dwordx2 v[58:59], v101, s[20:21] offset:3200
	global_load_dwordx2 v[60:61], v101, s[20:21] offset:3584
	global_load_dwordx2 v[62:63], v101, s[20:21] offset:3712
	s_branch .Lscan2_ld_done
.Lscan2_ld1:
	global_load_dwordx2 v[0:1], v101, s[20:21] offset:3584
	global_load_dwordx2 v[2:3], v101, s[20:21] offset:3712
	global_load_dwordx2 v[4:5], v101, s[20:21] offset:3072
	global_load_dwordx2 v[6:7], v101, s[20:21] offset:3200
	global_load_dwordx2 v[8:9], v101, s[20:21] offset:2560
	global_load_dwordx2 v[10:11], v101, s[20:21] offset:2688
	global_load_dwordx2 v[12:13], v101, s[20:21] offset:2048
	global_load_dwordx2 v[14:15], v101, s[20:21] offset:2176
	global_load_dwordx2 v[16:17], v101, s[20:21] offset:1536
	global_load_dwordx2 v[18:19], v101, s[20:21] offset:1664
	global_load_dwordx2 v[20:21], v101, s[20:21] offset:1024
	global_load_dwordx2 v[22:23], v101, s[20:21] offset:1152
	global_load_dwordx2 v[24:25], v101, s[20:21] offset:512
	global_load_dwordx2 v[26:27], v101, s[20:21] offset:640
	global_load_dwordx2 v[28:29], v101, s[20:21]
	global_load_dwordx2 v[30:31], v101, s[20:21] offset:128
	global_load_dwordx2 v[32:33], v100, s[20:21] offset:3584
	global_load_dwordx2 v[34:35], v100, s[20:21] offset:3712
	global_load_dwordx2 v[36:37], v100, s[20:21] offset:3072
	global_load_dwordx2 v[38:39], v100, s[20:21] offset:3200
	global_load_dwordx2 v[40:41], v100, s[20:21] offset:2560
	global_load_dwordx2 v[42:43], v100, s[20:21] offset:2688
	global_load_dwordx2 v[44:45], v100, s[20:21] offset:2048
	global_load_dwordx2 v[46:47], v100, s[20:21] offset:2176
	global_load_dwordx2 v[48:49], v100, s[20:21] offset:1536
	global_load_dwordx2 v[50:51], v100, s[20:21] offset:1664
	global_load_dwordx2 v[52:53], v100, s[20:21] offset:1024
	global_load_dwordx2 v[54:55], v100, s[20:21] offset:1152
	global_load_dwordx2 v[56:57], v100, s[20:21] offset:512
	global_load_dwordx2 v[58:59], v100, s[20:21] offset:640
	global_load_dwordx2 v[60:61], v100, s[20:21]
	global_load_dwordx2 v[62:63], v100, s[20:21] offset:128
; __device__ __forceinline__ void s5_scan_bg(LAS unsigned char* lds, const S5In P, const bf16_t* F, bf16_t* XB, int b, int g, const int tid) {
;     ...
;     float a1r[2], a1i[2], a16r[2], a16i[2];
; #pragma unroll
;     for (int di = 0; di < 2; ++di) { const int gp = (di * 64 + g) * 64 + p;
;         const float dt = expf(P.log_dt[di * 64 + g]); const float lr = P.lam_re[gp], li = P.lam_im[gp];
;         const float mag = expf(lr * dt), ang = li * dt; float ar = mag * cosf(ang), ai = mag * sinf(ang);
; #pragma unroll
;         for (int sq = 0; sq < 4; ++sq) { const float t = ar * ar - ai * ai; ai = 2.f * ar * ai; ar = t; }
;         a1r[di] = ar; a1i[di] = ai;
; #pragma unroll
;         for (int sq = 0; sq < 4; ++sq) { const float t = ar * ar - ai * ai; ai = 2.f * ar * ai; ar = t; }
;         a16r[di] = ar; a16i[di] = ai; }
.Lscan2_ld_done:
	s_lshl_b32 s29, s34, 15
	s_lshl_b32 s28, s16, 8
	s_add_i32 s29, s29, s28
	s_lshl_b32 s28, s27, 14
	s_add_i32 s29, s29, s28
	v_lshlrev_b32_e32 v102, 4, v162
	v_add_u32_e32 v102, s29, v102
	global_load_dwordx4 v[88:91], v102, s[8:9]
	global_load_dwordx4 v[92:95], v102, s[10:11]
	s_lshl_b32 s28, s34, 7
	s_add_i32 s28, s28, s16
	s_lshl_b32 s29, s27, 6
	s_add_i32 s28, s28, s29
	s_lshl_b32 s28, s28, 2
	s_add_u32 s12, s12, s28
	s_addc_u32 s13, s13, 0
	s_load_dword s30, s[12:13], 0x0
	v_mov_b32_e32 v96, 0x3fb8aa3b
	s_waitcnt lgkmcnt(0)
	v_mul_f32_e32 v97, s30, v96
	v_exp_f32_e32 v97, v97
	s_waitcnt vmcnt(0)
	v_mul_f32_e32 v98, v88, v97
	v_mul_f32_e32 v99, v92, v97
	v_mul_f32_e32 v98, v98, v96
	v_mul_f32_e32 v99, 0.15915494, v99
	v_exp_f32_e32 v98, v98
	v_fract_f32_e32 v99, v99
	s_nop 0
	v_cos_f32_e32 v104, v99
	v_sin_f32_e32 v105, v99
	s_nop 0
	v_mul_f32_e32 v72, v98, v104
	v_mul_f32_e32 v73, v98, v105
	v_mul_f32_e32 v106, v73, v73
	v_mul_f32_e32 v107, v72, v73
	v_fma_f32 v72, v72, v72, -v106
	v_add_f32_e32 v73, v107, v107
	v_mul_f32_e32 v106, v73, v73
	v_mul_f32_e32 v107, v72, v73
	v_fma_f32 v72, v72, v72, -v106
	v_add_f32_e32 v73, v107, v107
	v_mul_f32_e32 v106, v73, v73
	v_mul_f32_e32 v107, v72, v73
	v_fma_f32 v72, v72, v72, -v106
	v_add_f32_e32 v73, v107, v107
	v_mul_f32_e32 v106, v73, v73
	v_mul_f32_e32 v107, v72, v73
	v_fma_f32 v72, v72, v72, -v106
	v_add_f32_e32 v73, v107, v107
	v_mov_b32_e32 v80, v72
	v_mov_b32_e32 v81, v73
	v_mul_f32_e32 v106, v81, v81
	v_mul_f32_e32 v107, v80, v81
	v_fma_f32 v80, v80, v80, -v106
	v_add_f32_e32 v81, v107, v107
	v_mul_f32_e32 v106, v81, v81
	v_mul_f32_e32 v107, v80, v81
	v_fma_f32 v80, v80, v80, -v106
	v_add_f32_e32 v81, v107, v107
	v_mul_f32_e32 v106, v81, v81
	v_mul_f32_e32 v107, v80, v81
	v_fma_f32 v80, v80, v80, -v106
	v_add_f32_e32 v81, v107, v107
	v_mul_f32_e32 v106, v81, v81
	v_mul_f32_e32 v107, v80, v81
	v_fma_f32 v80, v80, v80, -v106
	v_add_f32_e32 v81, v107, v107
	v_mul_f32_e32 v98, v89, v97
	v_mul_f32_e32 v99, v93, v97
	v_mul_f32_e32 v98, v98, v96
	v_mul_f32_e32 v99, 0.15915494, v99
	v_exp_f32_e32 v98, v98
	v_fract_f32_e32 v99, v99
	s_nop 0
	v_cos_f32_e32 v104, v99
	v_sin_f32_e32 v105, v99
	s_nop 0
	v_mul_f32_e32 v74, v98, v104
	v_mul_f32_e32 v75, v98, v105
	v_mul_f32_e32 v106, v75, v75
	v_mul_f32_e32 v107, v74, v75
	v_fma_f32 v74, v74, v74, -v106
	v_add_f32_e32 v75, v107, v107
	v_mul_f32_e32 v106, v75, v75
	v_mul_f32_e32 v107, v74, v75
	v_fma_f32 v74, v74, v74, -v106
	v_add_f32_e32 v75, v107, v107
	v_mul_f32_e32 v106, v75, v75
	v_mul_f32_e32 v107, v74, v75
	v_fma_f32 v74, v74, v74, -v106
	v_add_f32_e32 v75, v107, v107
	v_mul_f32_e32 v106, v75, v75
	v_mul_f32_e32 v107, v74, v75
	v_fma_f32 v74, v74, v74, -v106
	v_add_f32_e32 v75, v107, v107
	v_mov_b32_e32 v82, v74
	v_mov_b32_e32 v83, v75
	v_mul_f32_e32 v106, v83, v83
	v_mul_f32_e32 v107, v82, v83
	v_fma_f32 v82, v82, v82, -v106
	v_add_f32_e32 v83, v107, v107
	v_mul_f32_e32 v106, v83, v83
	v_mul_f32_e32 v107, v82, v83
	v_fma_f32 v82, v82, v82, -v106
	v_add_f32_e32 v83, v107, v107
	v_mul_f32_e32 v106, v83, v83
	v_mul_f32_e32 v107, v82, v83
	v_fma_f32 v82, v82, v82, -v106
	v_add_f32_e32 v83, v107, v107
	v_mul_f32_e32 v106, v83, v83
	v_mul_f32_e32 v107, v82, v83
	v_fma_f32 v82, v82, v82, -v106
	v_add_f32_e32 v83, v107, v107
	v_mul_f32_e32 v98, v90, v97
	v_mul_f32_e32 v99, v94, v97
	v_mul_f32_e32 v98, v98, v96
	v_mul_f32_e32 v99, 0.15915494, v99
	v_exp_f32_e32 v98, v98
	v_fract_f32_e32 v99, v99
	s_nop 0
	v_cos_f32_e32 v104, v99
	v_sin_f32_e32 v105, v99
	s_nop 0
	v_mul_f32_e32 v76, v98, v104
	v_mul_f32_e32 v77, v98, v105
	v_mul_f32_e32 v106, v77, v77
	v_mul_f32_e32 v107, v76, v77
	v_fma_f32 v76, v76, v76, -v106
	v_add_f32_e32 v77, v107, v107
	v_mul_f32_e32 v106, v77, v77
	v_mul_f32_e32 v107, v76, v77
	v_fma_f32 v76, v76, v76, -v106
	v_add_f32_e32 v77, v107, v107
	v_mul_f32_e32 v106, v77, v77
	v_mul_f32_e32 v107, v76, v77
	v_fma_f32 v76, v76, v76, -v106
	v_add_f32_e32 v77, v107, v107
	v_mul_f32_e32 v106, v77, v77
	v_mul_f32_e32 v107, v76, v77
	v_fma_f32 v76, v76, v76, -v106
	v_add_f32_e32 v77, v107, v107
	v_mov_b32_e32 v84, v76
	v_mov_b32_e32 v85, v77
	v_mul_f32_e32 v106, v85, v85
	v_mul_f32_e32 v107, v84, v85
	v_fma_f32 v84, v84, v84, -v106
	v_add_f32_e32 v85, v107, v107
	v_mul_f32_e32 v106, v85, v85
	v_mul_f32_e32 v107, v84, v85
	v_fma_f32 v84, v84, v84, -v106
	v_add_f32_e32 v85, v107, v107
	v_mul_f32_e32 v106, v85, v85
	v_mul_f32_e32 v107, v84, v85
	v_fma_f32 v84, v84, v84, -v106
	v_add_f32_e32 v85, v107, v107
	v_mul_f32_e32 v106, v85, v85
	v_mul_f32_e32 v107, v84, v85
	v_fma_f32 v84, v84, v84, -v106
	v_add_f32_e32 v85, v107, v107
	v_mul_f32_e32 v98, v91, v97
	v_mul_f32_e32 v99, v95, v97
	v_mul_f32_e32 v98, v98, v96
	v_mul_f32_e32 v99, 0.15915494, v99
	v_exp_f32_e32 v98, v98
	v_fract_f32_e32 v99, v99
	s_nop 0
	v_cos_f32_e32 v104, v99
	v_sin_f32_e32 v105, v99
	s_nop 0
	v_mul_f32_e32 v78, v98, v104
	v_mul_f32_e32 v79, v98, v105
	v_mul_f32_e32 v106, v79, v79
	v_mul_f32_e32 v107, v78, v79
	v_fma_f32 v78, v78, v78, -v106
	v_add_f32_e32 v79, v107, v107
	v_mul_f32_e32 v106, v79, v79
	v_mul_f32_e32 v107, v78, v79
	v_fma_f32 v78, v78, v78, -v106
	v_add_f32_e32 v79, v107, v107
	v_mul_f32_e32 v106, v79, v79
	v_mul_f32_e32 v107, v78, v79
	v_fma_f32 v78, v78, v78, -v106
	v_add_f32_e32 v79, v107, v107
	v_mul_f32_e32 v106, v79, v79
	v_mul_f32_e32 v107, v78, v79
	v_fma_f32 v78, v78, v78, -v106
	v_add_f32_e32 v79, v107, v107
	v_mov_b32_e32 v86, v78
	v_mov_b32_e32 v87, v79
	v_mul_f32_e32 v106, v87, v87
	v_mul_f32_e32 v107, v86, v87
	v_fma_f32 v86, v86, v86, -v106
	v_add_f32_e32 v87, v107, v107
	v_mul_f32_e32 v106, v87, v87
	v_mul_f32_e32 v107, v86, v87
; __device__ __forceinline__ void s5_scan_bg(LAS unsigned char* lds, const S5In P, const bf16_t* F, bf16_t* XB, int b, int g, const int tid) {
;     ...
;     for (int jj = 0; jj < 4; ++jj) { const int job = wid + 8 * jj, di = job >> 4, seg = job & 15;
;         const float ar = di ? a1r[1] : a1r[0], ai = di ? a1i[1] : a1i[0]; float xr = 0.f, xi = 0.f;
; #pragma unroll
;         for (int j = 0; j < 16; ++j) { const float nxr = ar * xr - ai * xi + fr[jj][j], nxi = ar * xi + ai * xr + fi[jj][j]; xr = nxr; xi = nxi; }
;         E[(di * 16 + seg) * 64 + p] = (f32x2v){xr, xi}; }
	v_fma_f32 v86, v86, v86, -v106
	v_add_f32_e32 v87, v107, v107
	v_mul_f32_e32 v106, v87, v87
	v_mul_f32_e32 v107, v86, v87
	v_fma_f32 v86, v86, v86, -v106
	v_add_f32_e32 v87, v107, v107
	v_mul_f32_e32 v106, v87, v87
	v_mul_f32_e32 v107, v86, v87
	v_fma_f32 v86, v86, v86, -v106
	v_add_f32_e32 v87, v107, v107
	v_lshlrev_b32_e32 v64, 16, v0
	v_lshlrev_b32_e32 v65, 16, v2
	v_and_b32_e32 v66, 0xffff0000, v0
	v_and_b32_e32 v67, 0xffff0000, v2
	v_lshlrev_b32_e32 v68, 16, v1
	v_lshlrev_b32_e32 v69, 16, v3
	v_and_b32_e32 v70, 0xffff0000, v1
	v_and_b32_e32 v71, 0xffff0000, v3
	v_lshlrev_b32_e32 v104, 16, v4
	v_lshlrev_b32_e32 v105, 16, v6
	v_fma_f32 v104, v72, v64, v104
	v_fma_f32 v105, v72, v65, v105
	v_fma_f32 v104, -v73, v65, v104
	v_fma_f32 v65, v73, v64, v105
	v_mov_b32_e32 v64, v104
	v_and_b32_e32 v104, 0xffff0000, v4
	v_and_b32_e32 v105, 0xffff0000, v6
	v_fma_f32 v104, v74, v66, v104
	v_fma_f32 v105, v74, v67, v105
	v_fma_f32 v104, -v75, v67, v104
	v_fma_f32 v67, v75, v66, v105
	v_mov_b32_e32 v66, v104
	v_lshlrev_b32_e32 v104, 16, v5
	v_lshlrev_b32_e32 v105, 16, v7
	v_fma_f32 v104, v76, v68, v104
	v_fma_f32 v105, v76, v69, v105
	v_fma_f32 v104, -v77, v69, v104
	v_fma_f32 v69, v77, v68, v105
	v_mov_b32_e32 v68, v104
	v_and_b32_e32 v104, 0xffff0000, v5
	v_and_b32_e32 v105, 0xffff0000, v7
	v_fma_f32 v104, v78, v70, v104
	v_fma_f32 v105, v78, v71, v105
	v_fma_f32 v104, -v79, v71, v104
	v_fma_f32 v71, v79, v70, v105
	v_mov_b32_e32 v70, v104
	v_lshlrev_b32_e32 v104, 16, v8
	v_lshlrev_b32_e32 v105, 16, v10
	v_fma_f32 v104, v72, v64, v104
	v_fma_f32 v105, v72, v65, v105
	v_fma_f32 v104, -v73, v65, v104
	v_fma_f32 v65, v73, v64, v105
	v_mov_b32_e32 v64, v104
	v_and_b32_e32 v104, 0xffff0000, v8
	v_and_b32_e32 v105, 0xffff0000, v10
	v_fma_f32 v104, v74, v66, v104
	v_fma_f32 v105, v74, v67, v105
	v_fma_f32 v104, -v75, v67, v104
	v_fma_f32 v67, v75, v66, v105
	v_mov_b32_e32 v66, v104
	v_lshlrev_b32_e32 v104, 16, v9
	v_lshlrev_b32_e32 v105, 16, v11
	v_fma_f32 v104, v76, v68, v104
	v_fma_f32 v105, v76, v69, v105
	v_fma_f32 v104, -v77, v69, v104
	v_fma_f32 v69, v77, v68, v105
	v_mov_b32_e32 v68, v104
	v_and_b32_e32 v104, 0xffff0000, v9
	v_and_b32_e32 v105, 0xffff0000, v11
	v_fma_f32 v104, v78, v70, v104
	v_fma_f32 v105, v78, v71, v105
	v_fma_f32 v104, -v79, v71, v104
	v_fma_f32 v71, v79, v70, v105
	v_mov_b32_e32 v70, v104
	v_lshlrev_b32_e32 v104, 16, v12
	v_lshlrev_b32_e32 v105, 16, v14
	v_fma_f32 v104, v72, v64, v104
	v_fma_f32 v105, v72, v65, v105
	v_fma_f32 v104, -v73, v65, v104
	v_fma_f32 v65, v73, v64, v105
	v_mov_b32_e32 v64, v104
	v_and_b32_e32 v104, 0xffff0000, v12
	v_and_b32_e32 v105, 0xffff0000, v14
	v_fma_f32 v104, v74, v66, v104
	v_fma_f32 v105, v74, v67, v105
	v_fma_f32 v104, -v75, v67, v104
	v_fma_f32 v67, v75, v66, v105
	v_mov_b32_e32 v66, v104
	v_lshlrev_b32_e32 v104, 16, v13
	v_lshlrev_b32_e32 v105, 16, v15
	v_fma_f32 v104, v76, v68, v104
	v_fma_f32 v105, v76, v69, v105
	v_fma_f32 v104, -v77, v69, v104
	v_fma_f32 v69, v77, v68, v105
	v_mov_b32_e32 v68, v104
	v_and_b32_e32 v104, 0xffff0000, v13
	v_and_b32_e32 v105, 0xffff0000, v15
	v_fma_f32 v104, v78, v70, v104
	v_fma_f32 v105, v78, v71, v105
	v_fma_f32 v104, -v79, v71, v104
	v_fma_f32 v71, v79, v70, v105
	v_mov_b32_e32 v70, v104
	v_lshlrev_b32_e32 v104, 16, v16
	v_lshlrev_b32_e32 v105, 16, v18
	v_fma_f32 v104, v72, v64, v104
	v_fma_f32 v105, v72, v65, v105
	v_fma_f32 v104, -v73, v65, v104
	v_fma_f32 v65, v73, v64, v105
	v_mov_b32_e32 v64, v104
	v_and_b32_e32 v104, 0xffff0000, v16
	v_and_b32_e32 v105, 0xffff0000, v18
	v_fma_f32 v104, v74, v66, v104
	v_fma_f32 v105, v74, v67, v105
	v_fma_f32 v104, -v75, v67, v104
	v_fma_f32 v67, v75, v66, v105
	v_mov_b32_e32 v66, v104
	v_lshlrev_b32_e32 v104, 16, v17
	v_lshlrev_b32_e32 v105, 16, v19
	v_fma_f32 v104, v76, v68, v104
	v_fma_f32 v105, v76, v69, v105
	v_fma_f32 v104, -v77, v69, v104
	v_fma_f32 v69, v77, v68, v105
	v_mov_b32_e32 v68, v104
	v_and_b32_e32 v104, 0xffff0000, v17
	v_and_b32_e32 v105, 0xffff0000, v19
	v_fma_f32 v104, v78, v70, v104
	v_fma_f32 v105, v78, v71, v105
	v_fma_f32 v104, -v79, v71, v104
	v_fma_f32 v71, v79, v70, v105
	v_mov_b32_e32 v70, v104
	v_lshlrev_b32_e32 v104, 16, v20
	v_lshlrev_b32_e32 v105, 16, v22
	v_fma_f32 v104, v72, v64, v104
	v_fma_f32 v105, v72, v65, v105
	v_fma_f32 v104, -v73, v65, v104
	v_fma_f32 v65, v73, v64, v105
	v_mov_b32_e32 v64, v104
	v_and_b32_e32 v104, 0xffff0000, v20
	v_and_b32_e32 v105, 0xffff0000, v22
	v_fma_f32 v104, v74, v66, v104
	v_fma_f32 v105, v74, v67, v105
	v_fma_f32 v104, -v75, v67, v104
	v_fma_f32 v67, v75, v66, v105
	v_mov_b32_e32 v66, v104
	v_lshlrev_b32_e32 v104, 16, v21
	v_lshlrev_b32_e32 v105, 16, v23
	v_fma_f32 v104, v76, v68, v104
	v_fma_f32 v105, v76, v69, v105
	v_fma_f32 v104, -v77, v69, v104
	v_fma_f32 v69, v77, v68, v105
	v_mov_b32_e32 v68, v104
	v_and_b32_e32 v104, 0xffff0000, v21
	v_and_b32_e32 v105, 0xffff0000, v23
	v_fma_f32 v104, v78, v70, v104
	v_fma_f32 v105, v78, v71, v105
	v_fma_f32 v104, -v79, v71, v104
	v_fma_f32 v71, v79, v70, v105
	v_mov_b32_e32 v70, v104
	v_lshlrev_b32_e32 v104, 16, v24
	v_lshlrev_b32_e32 v105, 16, v26
	v_fma_f32 v104, v72, v64, v104
	v_fma_f32 v105, v72, v65, v105
	v_fma_f32 v104, -v73, v65, v104
	v_fma_f32 v65, v73, v64, v105
	v_mov_b32_e32 v64, v104
	v_and_b32_e32 v104, 0xffff0000, v24
	v_and_b32_e32 v105, 0xffff0000, v26
	v_fma_f32 v104, v74, v66, v104
	v_fma_f32 v105, v74, v67, v105
	v_fma_f32 v104, -v75, v67, v104
	v_fma_f32 v67, v75, v66, v105
	v_mov_b32_e32 v66, v104
	v_lshlrev_b32_e32 v104, 16, v25
	v_lshlrev_b32_e32 v105, 16, v27
	v_fma_f32 v104, v76, v68, v104
	v_fma_f32 v105, v76, v69, v105
	v_fma_f32 v104, -v77, v69, v104
; __device__ __forceinline__ void s5_scan_bg(LAS unsigned char* lds, const S5In P, const bf16_t* F, bf16_t* XB, int b, int g, const int tid) {
;     ...
;     for (int jj = 0; jj < 4; ++jj) { const int job = wid + 8 * jj, di = job >> 4, seg = job & 15;
;         const float ar = di ? a1r[1] : a1r[0], ai = di ? a1i[1] : a1i[0]; float xr = 0.f, xi = 0.f;
; #pragma unroll
;         for (int j = 0; j < 16; ++j) { const float nxr = ar * xr - ai * xi + fr[jj][j], nxi = ar * xi + ai * xr + fi[jj][j]; xr = nxr; xi = nxi; }
;         E[(di * 16 + seg) * 64 + p] = (f32x2v){xr, xi}; }
	v_fma_f32 v69, v77, v68, v105
	v_mov_b32_e32 v68, v104
	v_and_b32_e32 v104, 0xffff0000, v25
	v_and_b32_e32 v105, 0xffff0000, v27
	v_fma_f32 v104, v78, v70, v104
	v_fma_f32 v105, v78, v71, v105
	v_fma_f32 v104, -v79, v71, v104
	v_fma_f32 v71, v79, v70, v105
	v_mov_b32_e32 v70, v104
	v_lshlrev_b32_e32 v104, 16, v28
	v_lshlrev_b32_e32 v105, 16, v30
	v_fma_f32 v104, v72, v64, v104
	v_fma_f32 v105, v72, v65, v105
	v_fma_f32 v104, -v73, v65, v104
	v_fma_f32 v65, v73, v64, v105
	v_mov_b32_e32 v64, v104
	v_and_b32_e32 v104, 0xffff0000, v28
	v_and_b32_e32 v105, 0xffff0000, v30
	v_fma_f32 v104, v74, v66, v104
	v_fma_f32 v105, v74, v67, v105
	v_fma_f32 v104, -v75, v67, v104
	v_fma_f32 v67, v75, v66, v105
	v_mov_b32_e32 v66, v104
	v_lshlrev_b32_e32 v104, 16, v29
	v_lshlrev_b32_e32 v105, 16, v31
	v_fma_f32 v104, v76, v68, v104
	v_fma_f32 v105, v76, v69, v105
	v_fma_f32 v104, -v77, v69, v104
	v_fma_f32 v69, v77, v68, v105
	v_mov_b32_e32 v68, v104
	v_and_b32_e32 v104, 0xffff0000, v29
	v_and_b32_e32 v105, 0xffff0000, v31
	v_fma_f32 v104, v78, v70, v104
	v_fma_f32 v105, v78, v71, v105
	v_fma_f32 v104, -v79, v71, v104
	v_fma_f32 v71, v79, v70, v105
	v_mov_b32_e32 v70, v104
	v_lshlrev_b32_e32 v104, 16, v32
	v_lshlrev_b32_e32 v105, 16, v34
	v_fma_f32 v104, v72, v64, v104
	v_fma_f32 v105, v72, v65, v105
	v_fma_f32 v104, -v73, v65, v104
	v_fma_f32 v65, v73, v64, v105
	v_mov_b32_e32 v64, v104
	v_and_b32_e32 v104, 0xffff0000, v32
	v_and_b32_e32 v105, 0xffff0000, v34
	v_fma_f32 v104, v74, v66, v104
	v_fma_f32 v105, v74, v67, v105
	v_fma_f32 v104, -v75, v67, v104
	v_fma_f32 v67, v75, v66, v105
	v_mov_b32_e32 v66, v104
	v_lshlrev_b32_e32 v104, 16, v33
	v_lshlrev_b32_e32 v105, 16, v35
	v_fma_f32 v104, v76, v68, v104
	v_fma_f32 v105, v76, v69, v105
	v_fma_f32 v104, -v77, v69, v104
	v_fma_f32 v69, v77, v68, v105
	v_mov_b32_e32 v68, v104
	v_and_b32_e32 v104, 0xffff0000, v33
	v_and_b32_e32 v105, 0xffff0000, v35
	v_fma_f32 v104, v78, v70, v104
	v_fma_f32 v105, v78, v71, v105
	v_fma_f32 v104, -v79, v71, v104
	v_fma_f32 v71, v79, v70, v105
	v_mov_b32_e32 v70, v104
	v_lshlrev_b32_e32 v104, 16, v36
	v_lshlrev_b32_e32 v105, 16, v38
	v_fma_f32 v104, v72, v64, v104
	v_fma_f32 v105, v72, v65, v105
	v_fma_f32 v104, -v73, v65, v104
	v_fma_f32 v65, v73, v64, v105
	v_mov_b32_e32 v64, v104
	v_and_b32_e32 v104, 0xffff0000, v36
	v_and_b32_e32 v105, 0xffff0000, v38
	v_fma_f32 v104, v74, v66, v104
	v_fma_f32 v105, v74, v67, v105
	v_fma_f32 v104, -v75, v67, v104
	v_fma_f32 v67, v75, v66, v105
	v_mov_b32_e32 v66, v104
	v_lshlrev_b32_e32 v104, 16, v37
	v_lshlrev_b32_e32 v105, 16, v39
	v_fma_f32 v104, v76, v68, v104
	v_fma_f32 v105, v76, v69, v105
	v_fma_f32 v104, -v77, v69, v104
	v_fma_f32 v69, v77, v68, v105
	v_mov_b32_e32 v68, v104
	v_and_b32_e32 v104, 0xffff0000, v37
	v_and_b32_e32 v105, 0xffff0000, v39
	v_fma_f32 v104, v78, v70, v104
	v_fma_f32 v105, v78, v71, v105
	v_fma_f32 v104, -v79, v71, v104
	v_fma_f32 v71, v79, v70, v105
	v_mov_b32_e32 v70, v104
	v_lshlrev_b32_e32 v104, 16, v40
	v_lshlrev_b32_e32 v105, 16, v42
	v_fma_f32 v104, v72, v64, v104
	v_fma_f32 v105, v72, v65, v105
	v_fma_f32 v104, -v73, v65, v104
	v_fma_f32 v65, v73, v64, v105
	v_mov_b32_e32 v64, v104
	v_and_b32_e32 v104, 0xffff0000, v40
	v_and_b32_e32 v105, 0xffff0000, v42
	v_fma_f32 v104, v74, v66, v104
	v_fma_f32 v105, v74, v67, v105
	v_fma_f32 v104, -v75, v67, v104
	v_fma_f32 v67, v75, v66, v105
	v_mov_b32_e32 v66, v104
	v_lshlrev_b32_e32 v104, 16, v41
	v_lshlrev_b32_e32 v105, 16, v43
	v_fma_f32 v104, v76, v68, v104
	v_fma_f32 v105, v76, v69, v105
	v_fma_f32 v104, -v77, v69, v104
	v_fma_f32 v69, v77, v68, v105
	v_mov_b32_e32 v68, v104
	v_and_b32_e32 v104, 0xffff0000, v41
	v_and_b32_e32 v105, 0xffff0000, v43
	v_fma_f32 v104, v78, v70, v104
	v_fma_f32 v105, v78, v71, v105
	v_fma_f32 v104, -v79, v71, v104
	v_fma_f32 v71, v79, v70, v105
	v_mov_b32_e32 v70, v104
	v_lshlrev_b32_e32 v104, 16, v44
	v_lshlrev_b32_e32 v105, 16, v46
	v_fma_f32 v104, v72, v64, v104
	v_fma_f32 v105, v72, v65, v105
	v_fma_f32 v104, -v73, v65, v104
	v_fma_f32 v65, v73, v64, v105
	v_mov_b32_e32 v64, v104
	v_and_b32_e32 v104, 0xffff0000, v44
	v_and_b32_e32 v105, 0xffff0000, v46
	v_fma_f32 v104, v74, v66, v104
	v_fma_f32 v105, v74, v67, v105
	v_fma_f32 v104, -v75, v67, v104
	v_fma_f32 v67, v75, v66, v105
	v_mov_b32_e32 v66, v104
	v_lshlrev_b32_e32 v104, 16, v45
	v_lshlrev_b32_e32 v105, 16, v47
	v_fma_f32 v104, v76, v68, v104
	v_fma_f32 v105, v76, v69, v105
	v_fma_f32 v104, -v77, v69, v104
	v_fma_f32 v69, v77, v68, v105
	v_mov_b32_e32 v68, v104
	v_and_b32_e32 v104, 0xffff0000, v45
	v_and_b32_e32 v105, 0xffff0000, v47
	v_fma_f32 v104, v78, v70, v104
	v_fma_f32 v105, v78, v71, v105
	v_fma_f32 v104, -v79, v71, v104
	v_fma_f32 v71, v79, v70, v105
	v_mov_b32_e32 v70, v104
	v_lshlrev_b32_e32 v104, 16, v48
	v_lshlrev_b32_e32 v105, 16, v50
	v_fma_f32 v104, v72, v64, v104
	v_fma_f32 v105, v72, v65, v105
	v_fma_f32 v104, -v73, v65, v104
	v_fma_f32 v65, v73, v64, v105
	v_mov_b32_e32 v64, v104
	v_and_b32_e32 v104, 0xffff0000, v48
	v_and_b32_e32 v105, 0xffff0000, v50
	v_fma_f32 v104, v74, v66, v104
	v_fma_f32 v105, v74, v67, v105
	v_fma_f32 v104, -v75, v67, v104
	v_fma_f32 v67, v75, v66, v105
	v_mov_b32_e32 v66, v104
	v_lshlrev_b32_e32 v104, 16, v49
	v_lshlrev_b32_e32 v105, 16, v51
	v_fma_f32 v104, v76, v68, v104
	v_fma_f32 v105, v76, v69, v105
	v_fma_f32 v104, -v77, v69, v104
	v_fma_f32 v69, v77, v68, v105
	v_mov_b32_e32 v68, v104
	v_and_b32_e32 v104, 0xffff0000, v49
	v_and_b32_e32 v105, 0xffff0000, v51
	v_fma_f32 v104, v78, v70, v104
	v_fma_f32 v105, v78, v71, v105
	v_fma_f32 v104, -v79, v71, v104
	v_fma_f32 v71, v79, v70, v105
	v_mov_b32_e32 v70, v104
; #define LDS_WAIT() asm volatile("s_waitcnt lgkmcnt(0)" ::: "memory")
; __device__ __forceinline__ void s5_scan_bg(LAS unsigned char* lds, const S5In P, const bf16_t* F, bf16_t* XB, int b, int g, const int tid) {
;     ...
;         for (int j = 0; j < 16; ++j) { const float nxr = ar * xr - ai * xi + fr[jj][j], nxi = ar * xi + ai * xr + fi[jj][j]; xr = nxr; xi = nxi; }
;         E[(di * 16 + seg) * 64 + p] = (f32x2v){xr, xi}; }
;     LDS_WAIT(); __syncthreads();
;     if (tid < 128) { const int di = tid >> 6; const float ar = di ? a16r[1] : a16r[0], ai = di ? a16i[1] : a16i[0]; float xr = 0.f, xi = 0.f;
;         for (int seg = 0; seg < 16; ++seg) { XI[(di * 16 + seg) * 64 + p] = (f32x2v){xr, xi}; const f32x2v e = E[(di * 16 + seg) * 64 + p];
;             const float nxr = ar * xr - ai * xi + e.x, nxi = ar * xi + ai * xr + e.y; xr = nxr; xi = nxi; } }
;     LDS_WAIT(); __syncthreads();
	v_lshlrev_b32_e32 v104, 16, v52
	v_lshlrev_b32_e32 v105, 16, v54
	v_fma_f32 v104, v72, v64, v104
	v_fma_f32 v105, v72, v65, v105
	v_fma_f32 v104, -v73, v65, v104
	v_fma_f32 v65, v73, v64, v105
	v_mov_b32_e32 v64, v104
	v_and_b32_e32 v104, 0xffff0000, v52
	v_and_b32_e32 v105, 0xffff0000, v54
	v_fma_f32 v104, v74, v66, v104
	v_fma_f32 v105, v74, v67, v105
	v_fma_f32 v104, -v75, v67, v104
	v_fma_f32 v67, v75, v66, v105
	v_mov_b32_e32 v66, v104
	v_lshlrev_b32_e32 v104, 16, v53
	v_lshlrev_b32_e32 v105, 16, v55
	v_fma_f32 v104, v76, v68, v104
	v_fma_f32 v105, v76, v69, v105
	v_fma_f32 v104, -v77, v69, v104
	v_fma_f32 v69, v77, v68, v105
	v_mov_b32_e32 v68, v104
	v_and_b32_e32 v104, 0xffff0000, v53
	v_and_b32_e32 v105, 0xffff0000, v55
	v_fma_f32 v104, v78, v70, v104
	v_fma_f32 v105, v78, v71, v105
	v_fma_f32 v104, -v79, v71, v104
	v_fma_f32 v71, v79, v70, v105
	v_mov_b32_e32 v70, v104
	v_lshlrev_b32_e32 v104, 16, v56
	v_lshlrev_b32_e32 v105, 16, v58
	v_fma_f32 v104, v72, v64, v104
	v_fma_f32 v105, v72, v65, v105
	v_fma_f32 v104, -v73, v65, v104
	v_fma_f32 v65, v73, v64, v105
	v_mov_b32_e32 v64, v104
	v_and_b32_e32 v104, 0xffff0000, v56
	v_and_b32_e32 v105, 0xffff0000, v58
	v_fma_f32 v104, v74, v66, v104
	v_fma_f32 v105, v74, v67, v105
	v_fma_f32 v104, -v75, v67, v104
	v_fma_f32 v67, v75, v66, v105
	v_mov_b32_e32 v66, v104
	v_lshlrev_b32_e32 v104, 16, v57
	v_lshlrev_b32_e32 v105, 16, v59
	v_fma_f32 v104, v76, v68, v104
	v_fma_f32 v105, v76, v69, v105
	v_fma_f32 v104, -v77, v69, v104
	v_fma_f32 v69, v77, v68, v105
	v_mov_b32_e32 v68, v104
	v_and_b32_e32 v104, 0xffff0000, v57
	v_and_b32_e32 v105, 0xffff0000, v59
	v_fma_f32 v104, v78, v70, v104
	v_fma_f32 v105, v78, v71, v105
	v_fma_f32 v104, -v79, v71, v104
	v_fma_f32 v71, v79, v70, v105
	v_mov_b32_e32 v70, v104
	v_lshlrev_b32_e32 v104, 16, v60
	v_lshlrev_b32_e32 v105, 16, v62
	v_fma_f32 v104, v72, v64, v104
	v_fma_f32 v105, v72, v65, v105
	v_fma_f32 v104, -v73, v65, v104
	v_fma_f32 v65, v73, v64, v105
	v_mov_b32_e32 v64, v104
	v_and_b32_e32 v104, 0xffff0000, v60
	v_and_b32_e32 v105, 0xffff0000, v62
	v_fma_f32 v104, v74, v66, v104
	v_fma_f32 v105, v74, v67, v105
	v_fma_f32 v104, -v75, v67, v104
	v_fma_f32 v67, v75, v66, v105
	v_mov_b32_e32 v66, v104
	v_lshlrev_b32_e32 v104, 16, v61
	v_lshlrev_b32_e32 v105, 16, v63
	v_fma_f32 v104, v76, v68, v104
	v_fma_f32 v105, v76, v69, v105
	v_fma_f32 v104, -v77, v69, v104
	v_fma_f32 v69, v77, v68, v105
	v_mov_b32_e32 v68, v104
	v_and_b32_e32 v104, 0xffff0000, v61
	v_and_b32_e32 v105, 0xffff0000, v63
	v_fma_f32 v104, v78, v70, v104
	v_fma_f32 v105, v78, v71, v105
	v_fma_f32 v104, -v79, v71, v104
	v_fma_f32 v71, v79, v70, v105
	v_mov_b32_e32 v70, v104
	v_lshlrev_b32_e32 v103, 9, v163
	v_lshl_add_u32 v103, v162, 5, v103
	ds_write_b128 v103, v[64:67]
	ds_write_b128 v103, v[68:71] offset:16
	s_waitcnt lgkmcnt(0)
	s_barrier
	s_and_b32 s28, s26, 3
	s_cmp_eq_u32 s28, 0
	s_cbranch_scc0 .Lscan2_comb_done
	s_mov_b64 s[36:37], exec
	s_mov_b64 exec, 0xffff
	v_mov_b32_e32 v116, 0
	v_mov_b32_e32 v117, 0
	v_mov_b32_e32 v118, 0
	v_mov_b32_e32 v119, 0
	v_mov_b32_e32 v120, 0
	v_mov_b32_e32 v121, 0
	v_mov_b32_e32 v122, 0
	v_mov_b32_e32 v123, 0
	ds_read_b128 v[108:111], v103
	ds_read_b128 v[112:115], v103 offset:16
	ds_write_b128 v103, v[116:119] offset:16384
	ds_write_b128 v103, v[120:123] offset:16400
	s_waitcnt lgkmcnt(2)
	v_fma_f32 v104, v80, v116, v108
	v_fma_f32 v105, v80, v117, v109
	v_fma_f32 v104, -v81, v117, v104
	v_fma_f32 v117, v81, v116, v105
	v_mov_b32_e32 v116, v104
	v_fma_f32 v104, v82, v118, v110
	v_fma_f32 v105, v82, v119, v111
	v_fma_f32 v104, -v83, v119, v104
	v_fma_f32 v119, v83, v118, v105
	v_mov_b32_e32 v118, v104
	s_waitcnt lgkmcnt(2)
	v_fma_f32 v104, v84, v120, v112
	v_fma_f32 v105, v84, v121, v113
	v_fma_f32 v104, -v85, v121, v104
	v_fma_f32 v121, v85, v120, v105
	v_mov_b32_e32 v120, v104
	v_fma_f32 v104, v86, v122, v114
	v_fma_f32 v105, v86, v123, v115
	v_fma_f32 v104, -v87, v123, v104
	v_fma_f32 v123, v87, v122, v105
	v_mov_b32_e32 v122, v104
	ds_read_b128 v[108:111], v103 offset:512
	ds_read_b128 v[112:115], v103 offset:528
	ds_write_b128 v103, v[116:119] offset:16896
	ds_write_b128 v103, v[120:123] offset:16912
	s_waitcnt lgkmcnt(2)
	v_fma_f32 v104, v80, v116, v108
	v_fma_f32 v105, v80, v117, v109
	v_fma_f32 v104, -v81, v117, v104
	v_fma_f32 v117, v81, v116, v105
	v_mov_b32_e32 v116, v104
	v_fma_f32 v104, v82, v118, v110
	v_fma_f32 v105, v82, v119, v111
	v_fma_f32 v104, -v83, v119, v104
	v_fma_f32 v119, v83, v118, v105
	v_mov_b32_e32 v118, v104
	s_waitcnt lgkmcnt(2)
	v_fma_f32 v104, v84, v120, v112
	v_fma_f32 v105, v84, v121, v113
	v_fma_f32 v104, -v85, v121, v104
	v_fma_f32 v121, v85, v120, v105
	v_mov_b32_e32 v120, v104
	v_fma_f32 v104, v86, v122, v114
	v_fma_f32 v105, v86, v123, v115
	v_fma_f32 v104, -v87, v123, v104
	v_fma_f32 v123, v87, v122, v105
	v_mov_b32_e32 v122, v104
	ds_read_b128 v[108:111], v103 offset:1024
	ds_read_b128 v[112:115], v103 offset:1040
	ds_write_b128 v103, v[116:119] offset:17408
	ds_write_b128 v103, v[120:123] offset:17424
	s_waitcnt lgkmcnt(2)
	v_fma_f32 v104, v80, v116, v108
	v_fma_f32 v105, v80, v117, v109
	v_fma_f32 v104, -v81, v117, v104
	v_fma_f32 v117, v81, v116, v105
	v_mov_b32_e32 v116, v104
	v_fma_f32 v104, v82, v118, v110
	v_fma_f32 v105, v82, v119, v111
	v_fma_f32 v104, -v83, v119, v104
	v_fma_f32 v119, v83, v118, v105
	v_mov_b32_e32 v118, v104
	s_waitcnt lgkmcnt(2)
; __device__ __forceinline__ void s5_scan_bg(LAS unsigned char* lds, const S5In P, const bf16_t* F, bf16_t* XB, int b, int g, const int tid) {
;     ...
;     if (tid < 128) { const int di = tid >> 6; const float ar = di ? a16r[1] : a16r[0], ai = di ? a16i[1] : a16i[0]; float xr = 0.f, xi = 0.f;
;         for (int seg = 0; seg < 16; ++seg) { XI[(di * 16 + seg) * 64 + p] = (f32x2v){xr, xi}; const f32x2v e = E[(di * 16 + seg) * 64 + p];
;             const float nxr = ar * xr - ai * xi + e.x, nxi = ar * xi + ai * xr + e.y; xr = nxr; xi = nxi; } }
	v_fma_f32 v104, v84, v120, v112
	v_fma_f32 v105, v84, v121, v113
	v_fma_f32 v104, -v85, v121, v104
	v_fma_f32 v121, v85, v120, v105
	v_mov_b32_e32 v120, v104
	v_fma_f32 v104, v86, v122, v114
	v_fma_f32 v105, v86, v123, v115
	v_fma_f32 v104, -v87, v123, v104
	v_fma_f32 v123, v87, v122, v105
	v_mov_b32_e32 v122, v104
	ds_read_b128 v[108:111], v103 offset:1536
	ds_read_b128 v[112:115], v103 offset:1552
	ds_write_b128 v103, v[116:119] offset:17920
	ds_write_b128 v103, v[120:123] offset:17936
	s_waitcnt lgkmcnt(2)
	v_fma_f32 v104, v80, v116, v108
	v_fma_f32 v105, v80, v117, v109
	v_fma_f32 v104, -v81, v117, v104
	v_fma_f32 v117, v81, v116, v105
	v_mov_b32_e32 v116, v104
	v_fma_f32 v104, v82, v118, v110
	v_fma_f32 v105, v82, v119, v111
	v_fma_f32 v104, -v83, v119, v104
	v_fma_f32 v119, v83, v118, v105
	v_mov_b32_e32 v118, v104
	s_waitcnt lgkmcnt(2)
	v_fma_f32 v104, v84, v120, v112
	v_fma_f32 v105, v84, v121, v113
	v_fma_f32 v104, -v85, v121, v104
	v_fma_f32 v121, v85, v120, v105
	v_mov_b32_e32 v120, v104
	v_fma_f32 v104, v86, v122, v114
	v_fma_f32 v105, v86, v123, v115
	v_fma_f32 v104, -v87, v123, v104
	v_fma_f32 v123, v87, v122, v105
	v_mov_b32_e32 v122, v104
	ds_read_b128 v[108:111], v103 offset:2048
	ds_read_b128 v[112:115], v103 offset:2064
	ds_write_b128 v103, v[116:119] offset:18432
	ds_write_b128 v103, v[120:123] offset:18448
	s_waitcnt lgkmcnt(2)
	v_fma_f32 v104, v80, v116, v108
	v_fma_f32 v105, v80, v117, v109
	v_fma_f32 v104, -v81, v117, v104
	v_fma_f32 v117, v81, v116, v105
	v_mov_b32_e32 v116, v104
	v_fma_f32 v104, v82, v118, v110
	v_fma_f32 v105, v82, v119, v111
	v_fma_f32 v104, -v83, v119, v104
	v_fma_f32 v119, v83, v118, v105
	v_mov_b32_e32 v118, v104
	s_waitcnt lgkmcnt(2)
	v_fma_f32 v104, v84, v120, v112
	v_fma_f32 v105, v84, v121, v113
	v_fma_f32 v104, -v85, v121, v104
	v_fma_f32 v121, v85, v120, v105
	v_mov_b32_e32 v120, v104
	v_fma_f32 v104, v86, v122, v114
	v_fma_f32 v105, v86, v123, v115
	v_fma_f32 v104, -v87, v123, v104
	v_fma_f32 v123, v87, v122, v105
	v_mov_b32_e32 v122, v104
	ds_read_b128 v[108:111], v103 offset:2560
	ds_read_b128 v[112:115], v103 offset:2576
	ds_write_b128 v103, v[116:119] offset:18944
	ds_write_b128 v103, v[120:123] offset:18960
	s_waitcnt lgkmcnt(2)
	v_fma_f32 v104, v80, v116, v108
	v_fma_f32 v105, v80, v117, v109
	v_fma_f32 v104, -v81, v117, v104
	v_fma_f32 v117, v81, v116, v105
	v_mov_b32_e32 v116, v104
	v_fma_f32 v104, v82, v118, v110
	v_fma_f32 v105, v82, v119, v111
	v_fma_f32 v104, -v83, v119, v104
	v_fma_f32 v119, v83, v118, v105
	v_mov_b32_e32 v118, v104
	s_waitcnt lgkmcnt(2)
	v_fma_f32 v104, v84, v120, v112
	v_fma_f32 v105, v84, v121, v113
	v_fma_f32 v104, -v85, v121, v104
	v_fma_f32 v121, v85, v120, v105
	v_mov_b32_e32 v120, v104
	v_fma_f32 v104, v86, v122, v114
	v_fma_f32 v105, v86, v123, v115
	v_fma_f32 v104, -v87, v123, v104
	v_fma_f32 v123, v87, v122, v105
	v_mov_b32_e32 v122, v104
	ds_read_b128 v[108:111], v103 offset:3072
	ds_read_b128 v[112:115], v103 offset:3088
	ds_write_b128 v103, v[116:119] offset:19456
	ds_write_b128 v103, v[120:123] offset:19472
	s_waitcnt lgkmcnt(2)
	v_fma_f32 v104, v80, v116, v108
	v_fma_f32 v105, v80, v117, v109
	v_fma_f32 v104, -v81, v117, v104
	v_fma_f32 v117, v81, v116, v105
	v_mov_b32_e32 v116, v104
	v_fma_f32 v104, v82, v118, v110
	v_fma_f32 v105, v82, v119, v111
	v_fma_f32 v104, -v83, v119, v104
	v_fma_f32 v119, v83, v118, v105
	v_mov_b32_e32 v118, v104
	s_waitcnt lgkmcnt(2)
	v_fma_f32 v104, v84, v120, v112
	v_fma_f32 v105, v84, v121, v113
	v_fma_f32 v104, -v85, v121, v104
	v_fma_f32 v121, v85, v120, v105
	v_mov_b32_e32 v120, v104
	v_fma_f32 v104, v86, v122, v114
	v_fma_f32 v105, v86, v123, v115
	v_fma_f32 v104, -v87, v123, v104
	v_fma_f32 v123, v87, v122, v105
	v_mov_b32_e32 v122, v104
	ds_read_b128 v[108:111], v103 offset:3584
	ds_read_b128 v[112:115], v103 offset:3600
	ds_write_b128 v103, v[116:119] offset:19968
	ds_write_b128 v103, v[120:123] offset:19984
	s_waitcnt lgkmcnt(2)
	v_fma_f32 v104, v80, v116, v108
	v_fma_f32 v105, v80, v117, v109
	v_fma_f32 v104, -v81, v117, v104
	v_fma_f32 v117, v81, v116, v105
	v_mov_b32_e32 v116, v104
	v_fma_f32 v104, v82, v118, v110
	v_fma_f32 v105, v82, v119, v111
	v_fma_f32 v104, -v83, v119, v104
	v_fma_f32 v119, v83, v118, v105
	v_mov_b32_e32 v118, v104
	s_waitcnt lgkmcnt(2)
	v_fma_f32 v104, v84, v120, v112
	v_fma_f32 v105, v84, v121, v113
	v_fma_f32 v104, -v85, v121, v104
	v_fma_f32 v121, v85, v120, v105
	v_mov_b32_e32 v120, v104
	v_fma_f32 v104, v86, v122, v114
	v_fma_f32 v105, v86, v123, v115
	v_fma_f32 v104, -v87, v123, v104
	v_fma_f32 v123, v87, v122, v105
	v_mov_b32_e32 v122, v104
	ds_read_b128 v[108:111], v103 offset:4096
	ds_read_b128 v[112:115], v103 offset:4112
	ds_write_b128 v103, v[116:119] offset:20480
	ds_write_b128 v103, v[120:123] offset:20496
	s_waitcnt lgkmcnt(2)
	v_fma_f32 v104, v80, v116, v108
	v_fma_f32 v105, v80, v117, v109
	v_fma_f32 v104, -v81, v117, v104
	v_fma_f32 v117, v81, v116, v105
	v_mov_b32_e32 v116, v104
	v_fma_f32 v104, v82, v118, v110
	v_fma_f32 v105, v82, v119, v111
	v_fma_f32 v104, -v83, v119, v104
	v_fma_f32 v119, v83, v118, v105
	v_mov_b32_e32 v118, v104
	s_waitcnt lgkmcnt(2)
	v_fma_f32 v104, v84, v120, v112
	v_fma_f32 v105, v84, v121, v113
	v_fma_f32 v104, -v85, v121, v104
	v_fma_f32 v121, v85, v120, v105
	v_mov_b32_e32 v120, v104
	v_fma_f32 v104, v86, v122, v114
	v_fma_f32 v105, v86, v123, v115
	v_fma_f32 v104, -v87, v123, v104
	v_fma_f32 v123, v87, v122, v105
	v_mov_b32_e32 v122, v104
	ds_read_b128 v[108:111], v103 offset:4608
	ds_read_b128 v[112:115], v103 offset:4624
	ds_write_b128 v103, v[116:119] offset:20992
	ds_write_b128 v103, v[120:123] offset:21008
	s_waitcnt lgkmcnt(2)
; __device__ __forceinline__ void s5_scan_bg(LAS unsigned char* lds, const S5In P, const bf16_t* F, bf16_t* XB, int b, int g, const int tid) {
;     ...
;     if (tid < 128) { const int di = tid >> 6; const float ar = di ? a16r[1] : a16r[0], ai = di ? a16i[1] : a16i[0]; float xr = 0.f, xi = 0.f;
;         for (int seg = 0; seg < 16; ++seg) { XI[(di * 16 + seg) * 64 + p] = (f32x2v){xr, xi}; const f32x2v e = E[(di * 16 + seg) * 64 + p];
;             const float nxr = ar * xr - ai * xi + e.x, nxi = ar * xi + ai * xr + e.y; xr = nxr; xi = nxi; } }
	v_fma_f32 v104, v80, v116, v108
	v_fma_f32 v105, v80, v117, v109
	v_fma_f32 v104, -v81, v117, v104
	v_fma_f32 v117, v81, v116, v105
	v_mov_b32_e32 v116, v104
	v_fma_f32 v104, v82, v118, v110
	v_fma_f32 v105, v82, v119, v111
	v_fma_f32 v104, -v83, v119, v104
	v_fma_f32 v119, v83, v118, v105
	v_mov_b32_e32 v118, v104
	s_waitcnt lgkmcnt(2)
	v_fma_f32 v104, v84, v120, v112
	v_fma_f32 v105, v84, v121, v113
	v_fma_f32 v104, -v85, v121, v104
	v_fma_f32 v121, v85, v120, v105
	v_mov_b32_e32 v120, v104
	v_fma_f32 v104, v86, v122, v114
	v_fma_f32 v105, v86, v123, v115
	v_fma_f32 v104, -v87, v123, v104
	v_fma_f32 v123, v87, v122, v105
	v_mov_b32_e32 v122, v104
	ds_read_b128 v[108:111], v103 offset:5120
	ds_read_b128 v[112:115], v103 offset:5136
	ds_write_b128 v103, v[116:119] offset:21504
	ds_write_b128 v103, v[120:123] offset:21520
	s_waitcnt lgkmcnt(2)
	v_fma_f32 v104, v80, v116, v108
	v_fma_f32 v105, v80, v117, v109
	v_fma_f32 v104, -v81, v117, v104
	v_fma_f32 v117, v81, v116, v105
	v_mov_b32_e32 v116, v104
	v_fma_f32 v104, v82, v118, v110
	v_fma_f32 v105, v82, v119, v111
	v_fma_f32 v104, -v83, v119, v104
	v_fma_f32 v119, v83, v118, v105
	v_mov_b32_e32 v118, v104
	s_waitcnt lgkmcnt(2)
	v_fma_f32 v104, v84, v120, v112
	v_fma_f32 v105, v84, v121, v113
	v_fma_f32 v104, -v85, v121, v104
	v_fma_f32 v121, v85, v120, v105
	v_mov_b32_e32 v120, v104
	v_fma_f32 v104, v86, v122, v114
	v_fma_f32 v105, v86, v123, v115
	v_fma_f32 v104, -v87, v123, v104
	v_fma_f32 v123, v87, v122, v105
	v_mov_b32_e32 v122, v104
	ds_read_b128 v[108:111], v103 offset:5632
	ds_read_b128 v[112:115], v103 offset:5648
	ds_write_b128 v103, v[116:119] offset:22016
	ds_write_b128 v103, v[120:123] offset:22032
	s_waitcnt lgkmcnt(2)
	v_fma_f32 v104, v80, v116, v108
	v_fma_f32 v105, v80, v117, v109
	v_fma_f32 v104, -v81, v117, v104
	v_fma_f32 v117, v81, v116, v105
	v_mov_b32_e32 v116, v104
	v_fma_f32 v104, v82, v118, v110
	v_fma_f32 v105, v82, v119, v111
	v_fma_f32 v104, -v83, v119, v104
	v_fma_f32 v119, v83, v118, v105
	v_mov_b32_e32 v118, v104
	s_waitcnt lgkmcnt(2)
	v_fma_f32 v104, v84, v120, v112
	v_fma_f32 v105, v84, v121, v113
	v_fma_f32 v104, -v85, v121, v104
	v_fma_f32 v121, v85, v120, v105
	v_mov_b32_e32 v120, v104
	v_fma_f32 v104, v86, v122, v114
	v_fma_f32 v105, v86, v123, v115
	v_fma_f32 v104, -v87, v123, v104
	v_fma_f32 v123, v87, v122, v105
	v_mov_b32_e32 v122, v104
	ds_read_b128 v[108:111], v103 offset:6144
	ds_read_b128 v[112:115], v103 offset:6160
	ds_write_b128 v103, v[116:119] offset:22528
	ds_write_b128 v103, v[120:123] offset:22544
	s_waitcnt lgkmcnt(2)
	v_fma_f32 v104, v80, v116, v108
	v_fma_f32 v105, v80, v117, v109
	v_fma_f32 v104, -v81, v117, v104
	v_fma_f32 v117, v81, v116, v105
	v_mov_b32_e32 v116, v104
	v_fma_f32 v104, v82, v118, v110
	v_fma_f32 v105, v82, v119, v111
	v_fma_f32 v104, -v83, v119, v104
	v_fma_f32 v119, v83, v118, v105
	v_mov_b32_e32 v118, v104
	s_waitcnt lgkmcnt(2)
	v_fma_f32 v104, v84, v120, v112
	v_fma_f32 v105, v84, v121, v113
	v_fma_f32 v104, -v85, v121, v104
	v_fma_f32 v121, v85, v120, v105
	v_mov_b32_e32 v120, v104
	v_fma_f32 v104, v86, v122, v114
	v_fma_f32 v105, v86, v123, v115
	v_fma_f32 v104, -v87, v123, v104
	v_fma_f32 v123, v87, v122, v105
	v_mov_b32_e32 v122, v104
	ds_read_b128 v[108:111], v103 offset:6656
	ds_read_b128 v[112:115], v103 offset:6672
	ds_write_b128 v103, v[116:119] offset:23040
	ds_write_b128 v103, v[120:123] offset:23056
	s_waitcnt lgkmcnt(2)
	v_fma_f32 v104, v80, v116, v108
	v_fma_f32 v105, v80, v117, v109
	v_fma_f32 v104, -v81, v117, v104
	v_fma_f32 v117, v81, v116, v105
	v_mov_b32_e32 v116, v104
	v_fma_f32 v104, v82, v118, v110
	v_fma_f32 v105, v82, v119, v111
	v_fma_f32 v104, -v83, v119, v104
	v_fma_f32 v119, v83, v118, v105
	v_mov_b32_e32 v118, v104
	s_waitcnt lgkmcnt(2)
	v_fma_f32 v104, v84, v120, v112
	v_fma_f32 v105, v84, v121, v113
	v_fma_f32 v104, -v85, v121, v104
	v_fma_f32 v121, v85, v120, v105
	v_mov_b32_e32 v120, v104
	v_fma_f32 v104, v86, v122, v114
	v_fma_f32 v105, v86, v123, v115
	v_fma_f32 v104, -v87, v123, v104
	v_fma_f32 v123, v87, v122, v105
	v_mov_b32_e32 v122, v104
	ds_read_b128 v[108:111], v103 offset:7168
	ds_read_b128 v[112:115], v103 offset:7184
	ds_write_b128 v103, v[116:119] offset:23552
	ds_write_b128 v103, v[120:123] offset:23568
	s_waitcnt lgkmcnt(2)
	v_fma_f32 v104, v80, v116, v108
	v_fma_f32 v105, v80, v117, v109
	v_fma_f32 v104, -v81, v117, v104
	v_fma_f32 v117, v81, v116, v105
	v_mov_b32_e32 v116, v104
	v_fma_f32 v104, v82, v118, v110
	v_fma_f32 v105, v82, v119, v111
	v_fma_f32 v104, -v83, v119, v104
	v_fma_f32 v119, v83, v118, v105
	v_mov_b32_e32 v118, v104
	s_waitcnt lgkmcnt(2)
	v_fma_f32 v104, v84, v120, v112
	v_fma_f32 v105, v84, v121, v113
	v_fma_f32 v104, -v85, v121, v104
	v_fma_f32 v121, v85, v120, v105
	v_mov_b32_e32 v120, v104
	v_fma_f32 v104, v86, v122, v114
	v_fma_f32 v105, v86, v123, v115
	v_fma_f32 v104, -v87, v123, v104
	v_fma_f32 v123, v87, v122, v105
	v_mov_b32_e32 v122, v104
	ds_read_b128 v[108:111], v103 offset:7680
	ds_read_b128 v[112:115], v103 offset:7696
	ds_write_b128 v103, v[116:119] offset:24064
	ds_write_b128 v103, v[120:123] offset:24080
	s_waitcnt lgkmcnt(2)
	v_fma_f32 v104, v80, v116, v108
	v_fma_f32 v105, v80, v117, v109
	v_fma_f32 v104, -v81, v117, v104
	v_fma_f32 v117, v81, v116, v105
	v_mov_b32_e32 v116, v104
	v_fma_f32 v104, v82, v118, v110
	v_fma_f32 v105, v82, v119, v111
	v_fma_f32 v104, -v83, v119, v104
	v_fma_f32 v119, v83, v118, v105
	v_mov_b32_e32 v118, v104
	s_waitcnt lgkmcnt(2)
	v_fma_f32 v104, v84, v120, v112
	v_fma_f32 v105, v84, v121, v113
	v_fma_f32 v104, -v85, v121, v104
	v_fma_f32 v121, v85, v120, v105
	v_mov_b32_e32 v120, v104
	v_fma_f32 v104, v86, v122, v114
	v_fma_f32 v105, v86, v123, v115
	v_fma_f32 v104, -v87, v123, v104
	v_fma_f32 v123, v87, v122, v105
	v_mov_b32_e32 v122, v104
	s_waitcnt lgkmcnt(0)
	s_mov_b64 exec, s[36:37]
; __device__ __forceinline__ unsigned f2bf(float f) { unsigned u = __float_as_uint(f); return (u + 0x7fffu + ((u >> 16) & 1u)) >> 16; }
; #define LDS_WAIT() asm volatile("s_waitcnt lgkmcnt(0)" ::: "memory")
; __device__ __forceinline__ void s5_scan_bg(LAS unsigned char* lds, const S5In P, const bf16_t* F, bf16_t* XB, int b, int g, const int tid) {
;     ...
;     LDS_WAIT(); __syncthreads();
; #pragma unroll
;     for (int jj = 0; jj < 4; ++jj) { const int job = wid + 8 * jj, di = job >> 4, seg = job & 15;
;         const float ar = di ? a1r[1] : a1r[0], ai = di ? a1i[1] : a1i[0]; const f32x2v x0 = XI[(di * 16 + seg) * 64 + p]; float xr = x0.x, xi = x0.y;
;         bf16_t* xg = XB + ((size_t)g * 1024 + b * 256) * 256 + di * 128 + p;
; #pragma unroll
;         for (int j = 0; j < 16; ++j) { const int c = di == 0 ? seg * 16 + j : 255 - (seg * 16 + j);
;             xg[(size_t)c * 256] = (bf16_t)f2bf(xr); xg[(size_t)c * 256 + 64] = (bf16_t)f2bf(xi);
;             const float nxr = ar * xr - ai * xi + fr[jj][j], nxi = ar * xi + ai * xr + fi[jj][j]; xr = nxr; xi = nxi; } }
.Lscan2_comb_done:
	s_waitcnt lgkmcnt(0)
	s_barrier
	ds_read_b128 v[64:67], v103 offset:16384
	ds_read_b128 v[68:71], v103 offset:16400
	s_waitcnt lgkmcnt(0)
	s_cmp_eq_u32 s27, 0
	s_cbranch_scc0 .Lscan2_p2b
	v_cvt_pk_bf16_f32 v108, v64, v66
	v_cvt_pk_bf16_f32 v109, v68, v70
	v_cvt_pk_bf16_f32 v110, v65, v67
	v_cvt_pk_bf16_f32 v111, v69, v71
	global_store_dwordx2 v100, v[108:109], s[24:25]
	global_store_dwordx2 v100, v[110:111], s[24:25] offset:128
	v_lshlrev_b32_e32 v104, 16, v0
	v_lshlrev_b32_e32 v105, 16, v2
	v_fma_f32 v104, v72, v64, v104
	v_fma_f32 v105, v72, v65, v105
	v_fma_f32 v104, -v73, v65, v104
	v_fma_f32 v65, v73, v64, v105
	v_mov_b32_e32 v64, v104
	v_and_b32_e32 v104, 0xffff0000, v0
	v_and_b32_e32 v105, 0xffff0000, v2
	v_fma_f32 v104, v74, v66, v104
	v_fma_f32 v105, v74, v67, v105
	v_fma_f32 v104, -v75, v67, v104
	v_fma_f32 v67, v75, v66, v105
	v_mov_b32_e32 v66, v104
	v_lshlrev_b32_e32 v104, 16, v1
	v_lshlrev_b32_e32 v105, 16, v3
	v_fma_f32 v104, v76, v68, v104
	v_fma_f32 v105, v76, v69, v105
	v_fma_f32 v104, -v77, v69, v104
	v_fma_f32 v69, v77, v68, v105
	v_mov_b32_e32 v68, v104
	v_and_b32_e32 v104, 0xffff0000, v1
	v_and_b32_e32 v105, 0xffff0000, v3
	v_fma_f32 v104, v78, v70, v104
	v_fma_f32 v105, v78, v71, v105
	v_fma_f32 v104, -v79, v71, v104
	v_fma_f32 v71, v79, v70, v105
	v_mov_b32_e32 v70, v104
	v_cvt_pk_bf16_f32 v112, v64, v66
	v_cvt_pk_bf16_f32 v113, v68, v70
	v_cvt_pk_bf16_f32 v114, v65, v67
	v_cvt_pk_bf16_f32 v115, v69, v71
	global_store_dwordx2 v100, v[112:113], s[24:25] offset:512
	global_store_dwordx2 v100, v[114:115], s[24:25] offset:640
	v_lshlrev_b32_e32 v104, 16, v4
	v_lshlrev_b32_e32 v105, 16, v6
	v_fma_f32 v104, v72, v64, v104
	v_fma_f32 v105, v72, v65, v105
	v_fma_f32 v104, -v73, v65, v104
	v_fma_f32 v65, v73, v64, v105
	v_mov_b32_e32 v64, v104
	v_and_b32_e32 v104, 0xffff0000, v4
	v_and_b32_e32 v105, 0xffff0000, v6
	v_fma_f32 v104, v74, v66, v104
	v_fma_f32 v105, v74, v67, v105
	v_fma_f32 v104, -v75, v67, v104
	v_fma_f32 v67, v75, v66, v105
	v_mov_b32_e32 v66, v104
	v_lshlrev_b32_e32 v104, 16, v5
	v_lshlrev_b32_e32 v105, 16, v7
	v_fma_f32 v104, v76, v68, v104
	v_fma_f32 v105, v76, v69, v105
	v_fma_f32 v104, -v77, v69, v104
	v_fma_f32 v69, v77, v68, v105
	v_mov_b32_e32 v68, v104
	v_and_b32_e32 v104, 0xffff0000, v5
	v_and_b32_e32 v105, 0xffff0000, v7
	v_fma_f32 v104, v78, v70, v104
	v_fma_f32 v105, v78, v71, v105
	v_fma_f32 v104, -v79, v71, v104
	v_fma_f32 v71, v79, v70, v105
	v_mov_b32_e32 v70, v104
	v_cvt_pk_bf16_f32 v108, v64, v66
	v_cvt_pk_bf16_f32 v109, v68, v70
	v_cvt_pk_bf16_f32 v110, v65, v67
	v_cvt_pk_bf16_f32 v111, v69, v71
	global_store_dwordx2 v100, v[108:109], s[24:25] offset:1024
	global_store_dwordx2 v100, v[110:111], s[24:25] offset:1152
	v_lshlrev_b32_e32 v104, 16, v8
	v_lshlrev_b32_e32 v105, 16, v10
	v_fma_f32 v104, v72, v64, v104
	v_fma_f32 v105, v72, v65, v105
	v_fma_f32 v104, -v73, v65, v104
	v_fma_f32 v65, v73, v64, v105
	v_mov_b32_e32 v64, v104
	v_and_b32_e32 v104, 0xffff0000, v8
	v_and_b32_e32 v105, 0xffff0000, v10
	v_fma_f32 v104, v74, v66, v104
	v_fma_f32 v105, v74, v67, v105
	v_fma_f32 v104, -v75, v67, v104
	v_fma_f32 v67, v75, v66, v105
	v_mov_b32_e32 v66, v104
	v_lshlrev_b32_e32 v104, 16, v9
	v_lshlrev_b32_e32 v105, 16, v11
	v_fma_f32 v104, v76, v68, v104
	v_fma_f32 v105, v76, v69, v105
	v_fma_f32 v104, -v77, v69, v104
	v_fma_f32 v69, v77, v68, v105
	v_mov_b32_e32 v68, v104
	v_and_b32_e32 v104, 0xffff0000, v9
	v_and_b32_e32 v105, 0xffff0000, v11
	v_fma_f32 v104, v78, v70, v104
	v_fma_f32 v105, v78, v71, v105
	v_fma_f32 v104, -v79, v71, v104
	v_fma_f32 v71, v79, v70, v105
	v_mov_b32_e32 v70, v104
	v_cvt_pk_bf16_f32 v112, v64, v66
	v_cvt_pk_bf16_f32 v113, v68, v70
	v_cvt_pk_bf16_f32 v114, v65, v67
	v_cvt_pk_bf16_f32 v115, v69, v71
	global_store_dwordx2 v100, v[112:113], s[24:25] offset:1536
	global_store_dwordx2 v100, v[114:115], s[24:25] offset:1664
	v_lshlrev_b32_e32 v104, 16, v12
	v_lshlrev_b32_e32 v105, 16, v14
	v_fma_f32 v104, v72, v64, v104
	v_fma_f32 v105, v72, v65, v105
	v_fma_f32 v104, -v73, v65, v104
	v_fma_f32 v65, v73, v64, v105
	v_mov_b32_e32 v64, v104
	v_and_b32_e32 v104, 0xffff0000, v12
	v_and_b32_e32 v105, 0xffff0000, v14
	v_fma_f32 v104, v74, v66, v104
	v_fma_f32 v105, v74, v67, v105
	v_fma_f32 v104, -v75, v67, v104
	v_fma_f32 v67, v75, v66, v105
	v_mov_b32_e32 v66, v104
	v_lshlrev_b32_e32 v104, 16, v13
	v_lshlrev_b32_e32 v105, 16, v15
	v_fma_f32 v104, v76, v68, v104
	v_fma_f32 v105, v76, v69, v105
	v_fma_f32 v104, -v77, v69, v104
	v_fma_f32 v69, v77, v68, v105
	v_mov_b32_e32 v68, v104
	v_and_b32_e32 v104, 0xffff0000, v13
	v_and_b32_e32 v105, 0xffff0000, v15
	v_fma_f32 v104, v78, v70, v104
	v_fma_f32 v105, v78, v71, v105
	v_fma_f32 v104, -v79, v71, v104
	v_fma_f32 v71, v79, v70, v105
	v_mov_b32_e32 v70, v104
	v_cvt_pk_bf16_f32 v108, v64, v66
	v_cvt_pk_bf16_f32 v109, v68, v70
	v_cvt_pk_bf16_f32 v110, v65, v67
	v_cvt_pk_bf16_f32 v111, v69, v71
	global_store_dwordx2 v100, v[108:109], s[24:25] offset:2048
	global_store_dwordx2 v100, v[110:111], s[24:25] offset:2176
	v_lshlrev_b32_e32 v104, 16, v16
	v_lshlrev_b32_e32 v105, 16, v18
	v_fma_f32 v104, v72, v64, v104
	v_fma_f32 v105, v72, v65, v105
	v_fma_f32 v104, -v73, v65, v104
	v_fma_f32 v65, v73, v64, v105
	v_mov_b32_e32 v64, v104
	v_and_b32_e32 v104, 0xffff0000, v16
	v_and_b32_e32 v105, 0xffff0000, v18
	v_fma_f32 v104, v74, v66, v104
	v_fma_f32 v105, v74, v67, v105
	v_fma_f32 v104, -v75, v67, v104
	v_fma_f32 v67, v75, v66, v105
	v_mov_b32_e32 v66, v104
	v_lshlrev_b32_e32 v104, 16, v17
	v_lshlrev_b32_e32 v105, 16, v19
	v_fma_f32 v104, v76, v68, v104
	v_fma_f32 v105, v76, v69, v105
	v_fma_f32 v104, -v77, v69, v104
; __device__ __forceinline__ unsigned f2bf(float f) { unsigned u = __float_as_uint(f); return (u + 0x7fffu + ((u >> 16) & 1u)) >> 16; }
; __device__ __forceinline__ void s5_scan_bg(LAS unsigned char* lds, const S5In P, const bf16_t* F, bf16_t* XB, int b, int g, const int tid) {
;     ...
;     for (int jj = 0; jj < 4; ++jj) { const int job = wid + 8 * jj, di = job >> 4, seg = job & 15;
;         const float ar = di ? a1r[1] : a1r[0], ai = di ? a1i[1] : a1i[0]; const f32x2v x0 = XI[(di * 16 + seg) * 64 + p]; float xr = x0.x, xi = x0.y;
;         bf16_t* xg = XB + ((size_t)g * 1024 + b * 256) * 256 + di * 128 + p;
; #pragma unroll
;         for (int j = 0; j < 16; ++j) { const int c = di == 0 ? seg * 16 + j : 255 - (seg * 16 + j);
;             xg[(size_t)c * 256] = (bf16_t)f2bf(xr); xg[(size_t)c * 256 + 64] = (bf16_t)f2bf(xi);
;             const float nxr = ar * xr - ai * xi + fr[jj][j], nxi = ar * xi + ai * xr + fi[jj][j]; xr = nxr; xi = nxi; } }
	v_fma_f32 v69, v77, v68, v105
	v_mov_b32_e32 v68, v104
	v_and_b32_e32 v104, 0xffff0000, v17
	v_and_b32_e32 v105, 0xffff0000, v19
	v_fma_f32 v104, v78, v70, v104
	v_fma_f32 v105, v78, v71, v105
	v_fma_f32 v104, -v79, v71, v104
	v_fma_f32 v71, v79, v70, v105
	v_mov_b32_e32 v70, v104
	v_cvt_pk_bf16_f32 v112, v64, v66
	v_cvt_pk_bf16_f32 v113, v68, v70
	v_cvt_pk_bf16_f32 v114, v65, v67
	v_cvt_pk_bf16_f32 v115, v69, v71
	global_store_dwordx2 v100, v[112:113], s[24:25] offset:2560
	global_store_dwordx2 v100, v[114:115], s[24:25] offset:2688
	v_lshlrev_b32_e32 v104, 16, v20
	v_lshlrev_b32_e32 v105, 16, v22
	v_fma_f32 v104, v72, v64, v104
	v_fma_f32 v105, v72, v65, v105
	v_fma_f32 v104, -v73, v65, v104
	v_fma_f32 v65, v73, v64, v105
	v_mov_b32_e32 v64, v104
	v_and_b32_e32 v104, 0xffff0000, v20
	v_and_b32_e32 v105, 0xffff0000, v22
	v_fma_f32 v104, v74, v66, v104
	v_fma_f32 v105, v74, v67, v105
	v_fma_f32 v104, -v75, v67, v104
	v_fma_f32 v67, v75, v66, v105
	v_mov_b32_e32 v66, v104
	v_lshlrev_b32_e32 v104, 16, v21
	v_lshlrev_b32_e32 v105, 16, v23
	v_fma_f32 v104, v76, v68, v104
	v_fma_f32 v105, v76, v69, v105
	v_fma_f32 v104, -v77, v69, v104
	v_fma_f32 v69, v77, v68, v105
	v_mov_b32_e32 v68, v104
	v_and_b32_e32 v104, 0xffff0000, v21
	v_and_b32_e32 v105, 0xffff0000, v23
	v_fma_f32 v104, v78, v70, v104
	v_fma_f32 v105, v78, v71, v105
	v_fma_f32 v104, -v79, v71, v104
	v_fma_f32 v71, v79, v70, v105
	v_mov_b32_e32 v70, v104
	v_cvt_pk_bf16_f32 v108, v64, v66
	v_cvt_pk_bf16_f32 v109, v68, v70
	v_cvt_pk_bf16_f32 v110, v65, v67
	v_cvt_pk_bf16_f32 v111, v69, v71
	global_store_dwordx2 v100, v[108:109], s[24:25] offset:3072
	global_store_dwordx2 v100, v[110:111], s[24:25] offset:3200
	v_lshlrev_b32_e32 v104, 16, v24
	v_lshlrev_b32_e32 v105, 16, v26
	v_fma_f32 v104, v72, v64, v104
	v_fma_f32 v105, v72, v65, v105
	v_fma_f32 v104, -v73, v65, v104
	v_fma_f32 v65, v73, v64, v105
	v_mov_b32_e32 v64, v104
	v_and_b32_e32 v104, 0xffff0000, v24
	v_and_b32_e32 v105, 0xffff0000, v26
	v_fma_f32 v104, v74, v66, v104
	v_fma_f32 v105, v74, v67, v105
	v_fma_f32 v104, -v75, v67, v104
	v_fma_f32 v67, v75, v66, v105
	v_mov_b32_e32 v66, v104
	v_lshlrev_b32_e32 v104, 16, v25
	v_lshlrev_b32_e32 v105, 16, v27
	v_fma_f32 v104, v76, v68, v104
	v_fma_f32 v105, v76, v69, v105
	v_fma_f32 v104, -v77, v69, v104
	v_fma_f32 v69, v77, v68, v105
	v_mov_b32_e32 v68, v104
	v_and_b32_e32 v104, 0xffff0000, v25
	v_and_b32_e32 v105, 0xffff0000, v27
	v_fma_f32 v104, v78, v70, v104
	v_fma_f32 v105, v78, v71, v105
	v_fma_f32 v104, -v79, v71, v104
	v_fma_f32 v71, v79, v70, v105
	v_mov_b32_e32 v70, v104
	v_cvt_pk_bf16_f32 v112, v64, v66
	v_cvt_pk_bf16_f32 v113, v68, v70
	v_cvt_pk_bf16_f32 v114, v65, v67
	v_cvt_pk_bf16_f32 v115, v69, v71
	global_store_dwordx2 v100, v[112:113], s[24:25] offset:3584
	global_store_dwordx2 v100, v[114:115], s[24:25] offset:3712
	v_lshlrev_b32_e32 v104, 16, v28
	v_lshlrev_b32_e32 v105, 16, v30
	v_fma_f32 v104, v72, v64, v104
	v_fma_f32 v105, v72, v65, v105
	v_fma_f32 v104, -v73, v65, v104
	v_fma_f32 v65, v73, v64, v105
	v_mov_b32_e32 v64, v104
	v_and_b32_e32 v104, 0xffff0000, v28
	v_and_b32_e32 v105, 0xffff0000, v30
	v_fma_f32 v104, v74, v66, v104
	v_fma_f32 v105, v74, v67, v105
	v_fma_f32 v104, -v75, v67, v104
	v_fma_f32 v67, v75, v66, v105
	v_mov_b32_e32 v66, v104
	v_lshlrev_b32_e32 v104, 16, v29
	v_lshlrev_b32_e32 v105, 16, v31
	v_fma_f32 v104, v76, v68, v104
	v_fma_f32 v105, v76, v69, v105
	v_fma_f32 v104, -v77, v69, v104
	v_fma_f32 v69, v77, v68, v105
	v_mov_b32_e32 v68, v104
	v_and_b32_e32 v104, 0xffff0000, v29
	v_and_b32_e32 v105, 0xffff0000, v31
	v_fma_f32 v104, v78, v70, v104
	v_fma_f32 v105, v78, v71, v105
	v_fma_f32 v104, -v79, v71, v104
	v_fma_f32 v71, v79, v70, v105
	v_mov_b32_e32 v70, v104
	v_cvt_pk_bf16_f32 v108, v64, v66
	v_cvt_pk_bf16_f32 v109, v68, v70
	v_cvt_pk_bf16_f32 v110, v65, v67
	v_cvt_pk_bf16_f32 v111, v69, v71
	global_store_dwordx2 v101, v[108:109], s[24:25]
	global_store_dwordx2 v101, v[110:111], s[24:25] offset:128
	v_lshlrev_b32_e32 v104, 16, v32
	v_lshlrev_b32_e32 v105, 16, v34
	v_fma_f32 v104, v72, v64, v104
	v_fma_f32 v105, v72, v65, v105
	v_fma_f32 v104, -v73, v65, v104
	v_fma_f32 v65, v73, v64, v105
	v_mov_b32_e32 v64, v104
	v_and_b32_e32 v104, 0xffff0000, v32
	v_and_b32_e32 v105, 0xffff0000, v34
	v_fma_f32 v104, v74, v66, v104
	v_fma_f32 v105, v74, v67, v105
	v_fma_f32 v104, -v75, v67, v104
	v_fma_f32 v67, v75, v66, v105
	v_mov_b32_e32 v66, v104
	v_lshlrev_b32_e32 v104, 16, v33
	v_lshlrev_b32_e32 v105, 16, v35
	v_fma_f32 v104, v76, v68, v104
	v_fma_f32 v105, v76, v69, v105
	v_fma_f32 v104, -v77, v69, v104
	v_fma_f32 v69, v77, v68, v105
	v_mov_b32_e32 v68, v104
	v_and_b32_e32 v104, 0xffff0000, v33
	v_and_b32_e32 v105, 0xffff0000, v35
	v_fma_f32 v104, v78, v70, v104
	v_fma_f32 v105, v78, v71, v105
	v_fma_f32 v104, -v79, v71, v104
	v_fma_f32 v71, v79, v70, v105
	v_mov_b32_e32 v70, v104
	v_cvt_pk_bf16_f32 v112, v64, v66
	v_cvt_pk_bf16_f32 v113, v68, v70
	v_cvt_pk_bf16_f32 v114, v65, v67
	v_cvt_pk_bf16_f32 v115, v69, v71
	global_store_dwordx2 v101, v[112:113], s[24:25] offset:512
	global_store_dwordx2 v101, v[114:115], s[24:25] offset:640
	v_lshlrev_b32_e32 v104, 16, v36
	v_lshlrev_b32_e32 v105, 16, v38
	v_fma_f32 v104, v72, v64, v104
	v_fma_f32 v105, v72, v65, v105
	v_fma_f32 v104, -v73, v65, v104
	v_fma_f32 v65, v73, v64, v105
	v_mov_b32_e32 v64, v104
	v_and_b32_e32 v104, 0xffff0000, v36
	v_and_b32_e32 v105, 0xffff0000, v38
	v_fma_f32 v104, v74, v66, v104
	v_fma_f32 v105, v74, v67, v105
	v_fma_f32 v104, -v75, v67, v104
	v_fma_f32 v67, v75, v66, v105
	v_mov_b32_e32 v66, v104
	v_lshlrev_b32_e32 v104, 16, v37
	v_lshlrev_b32_e32 v105, 16, v39
; __device__ __forceinline__ unsigned f2bf(float f) { unsigned u = __float_as_uint(f); return (u + 0x7fffu + ((u >> 16) & 1u)) >> 16; }
; __device__ __forceinline__ void s5_scan_bg(LAS unsigned char* lds, const S5In P, const bf16_t* F, bf16_t* XB, int b, int g, const int tid) {
;     ...
;     for (int jj = 0; jj < 4; ++jj) { const int job = wid + 8 * jj, di = job >> 4, seg = job & 15;
;         const float ar = di ? a1r[1] : a1r[0], ai = di ? a1i[1] : a1i[0]; const f32x2v x0 = XI[(di * 16 + seg) * 64 + p]; float xr = x0.x, xi = x0.y;
;         bf16_t* xg = XB + ((size_t)g * 1024 + b * 256) * 256 + di * 128 + p;
; #pragma unroll
;         for (int j = 0; j < 16; ++j) { const int c = di == 0 ? seg * 16 + j : 255 - (seg * 16 + j);
;             xg[(size_t)c * 256] = (bf16_t)f2bf(xr); xg[(size_t)c * 256 + 64] = (bf16_t)f2bf(xi);
;             const float nxr = ar * xr - ai * xi + fr[jj][j], nxi = ar * xi + ai * xr + fi[jj][j]; xr = nxr; xi = nxi; } }
	v_fma_f32 v104, v76, v68, v104
	v_fma_f32 v105, v76, v69, v105
	v_fma_f32 v104, -v77, v69, v104
	v_fma_f32 v69, v77, v68, v105
	v_mov_b32_e32 v68, v104
	v_and_b32_e32 v104, 0xffff0000, v37
	v_and_b32_e32 v105, 0xffff0000, v39
	v_fma_f32 v104, v78, v70, v104
	v_fma_f32 v105, v78, v71, v105
	v_fma_f32 v104, -v79, v71, v104
	v_fma_f32 v71, v79, v70, v105
	v_mov_b32_e32 v70, v104
	v_cvt_pk_bf16_f32 v108, v64, v66
	v_cvt_pk_bf16_f32 v109, v68, v70
	v_cvt_pk_bf16_f32 v110, v65, v67
	v_cvt_pk_bf16_f32 v111, v69, v71
	global_store_dwordx2 v101, v[108:109], s[24:25] offset:1024
	global_store_dwordx2 v101, v[110:111], s[24:25] offset:1152
	v_lshlrev_b32_e32 v104, 16, v40
	v_lshlrev_b32_e32 v105, 16, v42
	v_fma_f32 v104, v72, v64, v104
	v_fma_f32 v105, v72, v65, v105
	v_fma_f32 v104, -v73, v65, v104
	v_fma_f32 v65, v73, v64, v105
	v_mov_b32_e32 v64, v104
	v_and_b32_e32 v104, 0xffff0000, v40
	v_and_b32_e32 v105, 0xffff0000, v42
	v_fma_f32 v104, v74, v66, v104
	v_fma_f32 v105, v74, v67, v105
	v_fma_f32 v104, -v75, v67, v104
	v_fma_f32 v67, v75, v66, v105
	v_mov_b32_e32 v66, v104
	v_lshlrev_b32_e32 v104, 16, v41
	v_lshlrev_b32_e32 v105, 16, v43
	v_fma_f32 v104, v76, v68, v104
	v_fma_f32 v105, v76, v69, v105
	v_fma_f32 v104, -v77, v69, v104
	v_fma_f32 v69, v77, v68, v105
	v_mov_b32_e32 v68, v104
	v_and_b32_e32 v104, 0xffff0000, v41
	v_and_b32_e32 v105, 0xffff0000, v43
	v_fma_f32 v104, v78, v70, v104
	v_fma_f32 v105, v78, v71, v105
	v_fma_f32 v104, -v79, v71, v104
	v_fma_f32 v71, v79, v70, v105
	v_mov_b32_e32 v70, v104
	v_cvt_pk_bf16_f32 v112, v64, v66
	v_cvt_pk_bf16_f32 v113, v68, v70
	v_cvt_pk_bf16_f32 v114, v65, v67
	v_cvt_pk_bf16_f32 v115, v69, v71
	global_store_dwordx2 v101, v[112:113], s[24:25] offset:1536
	global_store_dwordx2 v101, v[114:115], s[24:25] offset:1664
	v_lshlrev_b32_e32 v104, 16, v44
	v_lshlrev_b32_e32 v105, 16, v46
	v_fma_f32 v104, v72, v64, v104
	v_fma_f32 v105, v72, v65, v105
	v_fma_f32 v104, -v73, v65, v104
	v_fma_f32 v65, v73, v64, v105
	v_mov_b32_e32 v64, v104
	v_and_b32_e32 v104, 0xffff0000, v44
	v_and_b32_e32 v105, 0xffff0000, v46
	v_fma_f32 v104, v74, v66, v104
	v_fma_f32 v105, v74, v67, v105
	v_fma_f32 v104, -v75, v67, v104
	v_fma_f32 v67, v75, v66, v105
	v_mov_b32_e32 v66, v104
	v_lshlrev_b32_e32 v104, 16, v45
	v_lshlrev_b32_e32 v105, 16, v47
	v_fma_f32 v104, v76, v68, v104
	v_fma_f32 v105, v76, v69, v105
	v_fma_f32 v104, -v77, v69, v104
	v_fma_f32 v69, v77, v68, v105
	v_mov_b32_e32 v68, v104
	v_and_b32_e32 v104, 0xffff0000, v45
	v_and_b32_e32 v105, 0xffff0000, v47
	v_fma_f32 v104, v78, v70, v104
	v_fma_f32 v105, v78, v71, v105
	v_fma_f32 v104, -v79, v71, v104
	v_fma_f32 v71, v79, v70, v105
	v_mov_b32_e32 v70, v104
	v_cvt_pk_bf16_f32 v108, v64, v66
	v_cvt_pk_bf16_f32 v109, v68, v70
	v_cvt_pk_bf16_f32 v110, v65, v67
	v_cvt_pk_bf16_f32 v111, v69, v71
	global_store_dwordx2 v101, v[108:109], s[24:25] offset:2048
	global_store_dwordx2 v101, v[110:111], s[24:25] offset:2176
	v_lshlrev_b32_e32 v104, 16, v48
	v_lshlrev_b32_e32 v105, 16, v50
	v_fma_f32 v104, v72, v64, v104
	v_fma_f32 v105, v72, v65, v105
	v_fma_f32 v104, -v73, v65, v104
	v_fma_f32 v65, v73, v64, v105
	v_mov_b32_e32 v64, v104
	v_and_b32_e32 v104, 0xffff0000, v48
	v_and_b32_e32 v105, 0xffff0000, v50
	v_fma_f32 v104, v74, v66, v104
	v_fma_f32 v105, v74, v67, v105
	v_fma_f32 v104, -v75, v67, v104
	v_fma_f32 v67, v75, v66, v105
	v_mov_b32_e32 v66, v104
	v_lshlrev_b32_e32 v104, 16, v49
	v_lshlrev_b32_e32 v105, 16, v51
	v_fma_f32 v104, v76, v68, v104
	v_fma_f32 v105, v76, v69, v105
	v_fma_f32 v104, -v77, v69, v104
	v_fma_f32 v69, v77, v68, v105
	v_mov_b32_e32 v68, v104
	v_and_b32_e32 v104, 0xffff0000, v49
	v_and_b32_e32 v105, 0xffff0000, v51
	v_fma_f32 v104, v78, v70, v104
	v_fma_f32 v105, v78, v71, v105
	v_fma_f32 v104, -v79, v71, v104
	v_fma_f32 v71, v79, v70, v105
	v_mov_b32_e32 v70, v104
	v_cvt_pk_bf16_f32 v112, v64, v66
	v_cvt_pk_bf16_f32 v113, v68, v70
	v_cvt_pk_bf16_f32 v114, v65, v67
	v_cvt_pk_bf16_f32 v115, v69, v71
	global_store_dwordx2 v101, v[112:113], s[24:25] offset:2560
	global_store_dwordx2 v101, v[114:115], s[24:25] offset:2688
	v_lshlrev_b32_e32 v104, 16, v52
	v_lshlrev_b32_e32 v105, 16, v54
	v_fma_f32 v104, v72, v64, v104
	v_fma_f32 v105, v72, v65, v105
	v_fma_f32 v104, -v73, v65, v104
	v_fma_f32 v65, v73, v64, v105
	v_mov_b32_e32 v64, v104
	v_and_b32_e32 v104, 0xffff0000, v52
	v_and_b32_e32 v105, 0xffff0000, v54
	v_fma_f32 v104, v74, v66, v104
	v_fma_f32 v105, v74, v67, v105
	v_fma_f32 v104, -v75, v67, v104
	v_fma_f32 v67, v75, v66, v105
	v_mov_b32_e32 v66, v104
	v_lshlrev_b32_e32 v104, 16, v53
	v_lshlrev_b32_e32 v105, 16, v55
	v_fma_f32 v104, v76, v68, v104
	v_fma_f32 v105, v76, v69, v105
	v_fma_f32 v104, -v77, v69, v104
	v_fma_f32 v69, v77, v68, v105
	v_mov_b32_e32 v68, v104
	v_and_b32_e32 v104, 0xffff0000, v53
	v_and_b32_e32 v105, 0xffff0000, v55
	v_fma_f32 v104, v78, v70, v104
	v_fma_f32 v105, v78, v71, v105
	v_fma_f32 v104, -v79, v71, v104
	v_fma_f32 v71, v79, v70, v105
	v_mov_b32_e32 v70, v104
	v_cvt_pk_bf16_f32 v108, v64, v66
	v_cvt_pk_bf16_f32 v109, v68, v70
	v_cvt_pk_bf16_f32 v110, v65, v67
	v_cvt_pk_bf16_f32 v111, v69, v71
	global_store_dwordx2 v101, v[108:109], s[24:25] offset:3072
	global_store_dwordx2 v101, v[110:111], s[24:25] offset:3200
	v_lshlrev_b32_e32 v104, 16, v56
	v_lshlrev_b32_e32 v105, 16, v58
	v_fma_f32 v104, v72, v64, v104
	v_fma_f32 v105, v72, v65, v105
	v_fma_f32 v104, -v73, v65, v104
	v_fma_f32 v65, v73, v64, v105
	v_mov_b32_e32 v64, v104
	v_and_b32_e32 v104, 0xffff0000, v56
	v_and_b32_e32 v105, 0xffff0000, v58
	v_fma_f32 v104, v74, v66, v104
	v_fma_f32 v105, v74, v67, v105
	v_fma_f32 v104, -v75, v67, v104
	v_fma_f32 v67, v75, v66, v105
	v_mov_b32_e32 v66, v104
	v_lshlrev_b32_e32 v104, 16, v57
	v_lshlrev_b32_e32 v105, 16, v59
	v_fma_f32 v104, v76, v68, v104
	v_fma_f32 v105, v76, v69, v105
	v_fma_f32 v104, -v77, v69, v104
	v_fma_f32 v69, v77, v68, v105
	v_mov_b32_e32 v68, v104
	v_and_b32_e32 v104, 0xffff0000, v57
	v_and_b32_e32 v105, 0xffff0000, v59
	v_fma_f32 v104, v78, v70, v104
	v_fma_f32 v105, v78, v71, v105
	v_fma_f32 v104, -v79, v71, v104
	v_fma_f32 v71, v79, v70, v105
	v_mov_b32_e32 v70, v104
	v_cvt_pk_bf16_f32 v112, v64, v66
	v_cvt_pk_bf16_f32 v113, v68, v70
	v_cvt_pk_bf16_f32 v114, v65, v67
	v_cvt_pk_bf16_f32 v115, v69, v71
	global_store_dwordx2 v101, v[112:113], s[24:25] offset:3584
	global_store_dwordx2 v101, v[114:115], s[24:25] offset:3712
	s_branch .LBB0_820
; __device__ __forceinline__ unsigned f2bf(float f) { unsigned u = __float_as_uint(f); return (u + 0x7fffu + ((u >> 16) & 1u)) >> 16; }
; __device__ __forceinline__ void s5_scan_bg(LAS unsigned char* lds, const S5In P, const bf16_t* F, bf16_t* XB, int b, int g, const int tid) {
;     ...
;     for (int jj = 0; jj < 4; ++jj) { const int job = wid + 8 * jj, di = job >> 4, seg = job & 15;
;         const float ar = di ? a1r[1] : a1r[0], ai = di ? a1i[1] : a1i[0]; const f32x2v x0 = XI[(di * 16 + seg) * 64 + p]; float xr = x0.x, xi = x0.y;
;         bf16_t* xg = XB + ((size_t)g * 1024 + b * 256) * 256 + di * 128 + p;
; #pragma unroll
;         for (int j = 0; j < 16; ++j) { const int c = di == 0 ? seg * 16 + j : 255 - (seg * 16 + j);
;             xg[(size_t)c * 256] = (bf16_t)f2bf(xr); xg[(size_t)c * 256 + 64] = (bf16_t)f2bf(xi);
;             const float nxr = ar * xr - ai * xi + fr[jj][j], nxi = ar * xi + ai * xr + fi[jj][j]; xr = nxr; xi = nxi; } }
.Lscan2_p2b:
	v_cvt_pk_bf16_f32 v108, v64, v66
	v_cvt_pk_bf16_f32 v109, v68, v70
	v_cvt_pk_bf16_f32 v110, v65, v67
	v_cvt_pk_bf16_f32 v111, v69, v71
	global_store_dwordx2 v101, v[108:109], s[24:25] offset:3584
	global_store_dwordx2 v101, v[110:111], s[24:25] offset:3712
	v_lshlrev_b32_e32 v104, 16, v0
	v_lshlrev_b32_e32 v105, 16, v2
	v_fma_f32 v104, v72, v64, v104
	v_fma_f32 v105, v72, v65, v105
	v_fma_f32 v104, -v73, v65, v104
	v_fma_f32 v65, v73, v64, v105
	v_mov_b32_e32 v64, v104
	v_and_b32_e32 v104, 0xffff0000, v0
	v_and_b32_e32 v105, 0xffff0000, v2
	v_fma_f32 v104, v74, v66, v104
	v_fma_f32 v105, v74, v67, v105
	v_fma_f32 v104, -v75, v67, v104
	v_fma_f32 v67, v75, v66, v105
	v_mov_b32_e32 v66, v104
	v_lshlrev_b32_e32 v104, 16, v1
	v_lshlrev_b32_e32 v105, 16, v3
	v_fma_f32 v104, v76, v68, v104
	v_fma_f32 v105, v76, v69, v105
	v_fma_f32 v104, -v77, v69, v104
	v_fma_f32 v69, v77, v68, v105
	v_mov_b32_e32 v68, v104
	v_and_b32_e32 v104, 0xffff0000, v1
	v_and_b32_e32 v105, 0xffff0000, v3
	v_fma_f32 v104, v78, v70, v104
	v_fma_f32 v105, v78, v71, v105
	v_fma_f32 v104, -v79, v71, v104
	v_fma_f32 v71, v79, v70, v105
	v_mov_b32_e32 v70, v104
	v_cvt_pk_bf16_f32 v112, v64, v66
	v_cvt_pk_bf16_f32 v113, v68, v70
	v_cvt_pk_bf16_f32 v114, v65, v67
	v_cvt_pk_bf16_f32 v115, v69, v71
	global_store_dwordx2 v101, v[112:113], s[24:25] offset:3072
	global_store_dwordx2 v101, v[114:115], s[24:25] offset:3200
	v_lshlrev_b32_e32 v104, 16, v4
	v_lshlrev_b32_e32 v105, 16, v6
	v_fma_f32 v104, v72, v64, v104
	v_fma_f32 v105, v72, v65, v105
	v_fma_f32 v104, -v73, v65, v104
	v_fma_f32 v65, v73, v64, v105
	v_mov_b32_e32 v64, v104
	v_and_b32_e32 v104, 0xffff0000, v4
	v_and_b32_e32 v105, 0xffff0000, v6
	v_fma_f32 v104, v74, v66, v104
	v_fma_f32 v105, v74, v67, v105
	v_fma_f32 v104, -v75, v67, v104
	v_fma_f32 v67, v75, v66, v105
	v_mov_b32_e32 v66, v104
	v_lshlrev_b32_e32 v104, 16, v5
	v_lshlrev_b32_e32 v105, 16, v7
	v_fma_f32 v104, v76, v68, v104
	v_fma_f32 v105, v76, v69, v105
	v_fma_f32 v104, -v77, v69, v104
	v_fma_f32 v69, v77, v68, v105
	v_mov_b32_e32 v68, v104
	v_and_b32_e32 v104, 0xffff0000, v5
	v_and_b32_e32 v105, 0xffff0000, v7
	v_fma_f32 v104, v78, v70, v104
	v_fma_f32 v105, v78, v71, v105
	v_fma_f32 v104, -v79, v71, v104
	v_fma_f32 v71, v79, v70, v105
	v_mov_b32_e32 v70, v104
	v_cvt_pk_bf16_f32 v108, v64, v66
	v_cvt_pk_bf16_f32 v109, v68, v70
	v_cvt_pk_bf16_f32 v110, v65, v67
	v_cvt_pk_bf16_f32 v111, v69, v71
	global_store_dwordx2 v101, v[108:109], s[24:25] offset:2560
	global_store_dwordx2 v101, v[110:111], s[24:25] offset:2688
	v_lshlrev_b32_e32 v104, 16, v8
	v_lshlrev_b32_e32 v105, 16, v10
	v_fma_f32 v104, v72, v64, v104
	v_fma_f32 v105, v72, v65, v105
	v_fma_f32 v104, -v73, v65, v104
	v_fma_f32 v65, v73, v64, v105
	v_mov_b32_e32 v64, v104
	v_and_b32_e32 v104, 0xffff0000, v8
	v_and_b32_e32 v105, 0xffff0000, v10
	v_fma_f32 v104, v74, v66, v104
	v_fma_f32 v105, v74, v67, v105
	v_fma_f32 v104, -v75, v67, v104
	v_fma_f32 v67, v75, v66, v105
	v_mov_b32_e32 v66, v104
	v_lshlrev_b32_e32 v104, 16, v9
	v_lshlrev_b32_e32 v105, 16, v11
	v_fma_f32 v104, v76, v68, v104
	v_fma_f32 v105, v76, v69, v105
	v_fma_f32 v104, -v77, v69, v104
	v_fma_f32 v69, v77, v68, v105
	v_mov_b32_e32 v68, v104
	v_and_b32_e32 v104, 0xffff0000, v9
	v_and_b32_e32 v105, 0xffff0000, v11
	v_fma_f32 v104, v78, v70, v104
	v_fma_f32 v105, v78, v71, v105
	v_fma_f32 v104, -v79, v71, v104
	v_fma_f32 v71, v79, v70, v105
	v_mov_b32_e32 v70, v104
	v_cvt_pk_bf16_f32 v112, v64, v66
	v_cvt_pk_bf16_f32 v113, v68, v70
	v_cvt_pk_bf16_f32 v114, v65, v67
	v_cvt_pk_bf16_f32 v115, v69, v71
	global_store_dwordx2 v101, v[112:113], s[24:25] offset:2048
	global_store_dwordx2 v101, v[114:115], s[24:25] offset:2176
	v_lshlrev_b32_e32 v104, 16, v12
	v_lshlrev_b32_e32 v105, 16, v14
	v_fma_f32 v104, v72, v64, v104
	v_fma_f32 v105, v72, v65, v105
	v_fma_f32 v104, -v73, v65, v104
	v_fma_f32 v65, v73, v64, v105
	v_mov_b32_e32 v64, v104
	v_and_b32_e32 v104, 0xffff0000, v12
	v_and_b32_e32 v105, 0xffff0000, v14
	v_fma_f32 v104, v74, v66, v104
	v_fma_f32 v105, v74, v67, v105
	v_fma_f32 v104, -v75, v67, v104
	v_fma_f32 v67, v75, v66, v105
	v_mov_b32_e32 v66, v104
	v_lshlrev_b32_e32 v104, 16, v13
	v_lshlrev_b32_e32 v105, 16, v15
	v_fma_f32 v104, v76, v68, v104
	v_fma_f32 v105, v76, v69, v105
	v_fma_f32 v104, -v77, v69, v104
	v_fma_f32 v69, v77, v68, v105
	v_mov_b32_e32 v68, v104
	v_and_b32_e32 v104, 0xffff0000, v13
	v_and_b32_e32 v105, 0xffff0000, v15
	v_fma_f32 v104, v78, v70, v104
	v_fma_f32 v105, v78, v71, v105
	v_fma_f32 v104, -v79, v71, v104
	v_fma_f32 v71, v79, v70, v105
	v_mov_b32_e32 v70, v104
	v_cvt_pk_bf16_f32 v108, v64, v66
	v_cvt_pk_bf16_f32 v109, v68, v70
	v_cvt_pk_bf16_f32 v110, v65, v67
	v_cvt_pk_bf16_f32 v111, v69, v71
	global_store_dwordx2 v101, v[108:109], s[24:25] offset:1536
	global_store_dwordx2 v101, v[110:111], s[24:25] offset:1664
	v_lshlrev_b32_e32 v104, 16, v16
	v_lshlrev_b32_e32 v105, 16, v18
	v_fma_f32 v104, v72, v64, v104
	v_fma_f32 v105, v72, v65, v105
	v_fma_f32 v104, -v73, v65, v104
	v_fma_f32 v65, v73, v64, v105
	v_mov_b32_e32 v64, v104
	v_and_b32_e32 v104, 0xffff0000, v16
	v_and_b32_e32 v105, 0xffff0000, v18
	v_fma_f32 v104, v74, v66, v104
	v_fma_f32 v105, v74, v67, v105
	v_fma_f32 v104, -v75, v67, v104
	v_fma_f32 v67, v75, v66, v105
	v_mov_b32_e32 v66, v104
	v_lshlrev_b32_e32 v104, 16, v17
	v_lshlrev_b32_e32 v105, 16, v19
	v_fma_f32 v104, v76, v68, v104
	v_fma_f32 v105, v76, v69, v105
	v_fma_f32 v104, -v77, v69, v104
	v_fma_f32 v69, v77, v68, v105
	v_mov_b32_e32 v68, v104
	v_and_b32_e32 v104, 0xffff0000, v17
	v_and_b32_e32 v105, 0xffff0000, v19
	v_fma_f32 v104, v78, v70, v104
	v_fma_f32 v105, v78, v71, v105
; __device__ __forceinline__ unsigned f2bf(float f) { unsigned u = __float_as_uint(f); return (u + 0x7fffu + ((u >> 16) & 1u)) >> 16; }
; __device__ __forceinline__ void s5_scan_bg(LAS unsigned char* lds, const S5In P, const bf16_t* F, bf16_t* XB, int b, int g, const int tid) {
;     ...
;     for (int jj = 0; jj < 4; ++jj) { const int job = wid + 8 * jj, di = job >> 4, seg = job & 15;
;         const float ar = di ? a1r[1] : a1r[0], ai = di ? a1i[1] : a1i[0]; const f32x2v x0 = XI[(di * 16 + seg) * 64 + p]; float xr = x0.x, xi = x0.y;
;         bf16_t* xg = XB + ((size_t)g * 1024 + b * 256) * 256 + di * 128 + p;
; #pragma unroll
;         for (int j = 0; j < 16; ++j) { const int c = di == 0 ? seg * 16 + j : 255 - (seg * 16 + j);
;             xg[(size_t)c * 256] = (bf16_t)f2bf(xr); xg[(size_t)c * 256 + 64] = (bf16_t)f2bf(xi);
;             const float nxr = ar * xr - ai * xi + fr[jj][j], nxi = ar * xi + ai * xr + fi[jj][j]; xr = nxr; xi = nxi; } }
	v_fma_f32 v104, -v79, v71, v104
	v_fma_f32 v71, v79, v70, v105
	v_mov_b32_e32 v70, v104
	v_cvt_pk_bf16_f32 v112, v64, v66
	v_cvt_pk_bf16_f32 v113, v68, v70
	v_cvt_pk_bf16_f32 v114, v65, v67
	v_cvt_pk_bf16_f32 v115, v69, v71
	global_store_dwordx2 v101, v[112:113], s[24:25] offset:1024
	global_store_dwordx2 v101, v[114:115], s[24:25] offset:1152
	v_lshlrev_b32_e32 v104, 16, v20
	v_lshlrev_b32_e32 v105, 16, v22
	v_fma_f32 v104, v72, v64, v104
	v_fma_f32 v105, v72, v65, v105
	v_fma_f32 v104, -v73, v65, v104
	v_fma_f32 v65, v73, v64, v105
	v_mov_b32_e32 v64, v104
	v_and_b32_e32 v104, 0xffff0000, v20
	v_and_b32_e32 v105, 0xffff0000, v22
	v_fma_f32 v104, v74, v66, v104
	v_fma_f32 v105, v74, v67, v105
	v_fma_f32 v104, -v75, v67, v104
	v_fma_f32 v67, v75, v66, v105
	v_mov_b32_e32 v66, v104
	v_lshlrev_b32_e32 v104, 16, v21
	v_lshlrev_b32_e32 v105, 16, v23
	v_fma_f32 v104, v76, v68, v104
	v_fma_f32 v105, v76, v69, v105
	v_fma_f32 v104, -v77, v69, v104
	v_fma_f32 v69, v77, v68, v105
	v_mov_b32_e32 v68, v104
	v_and_b32_e32 v104, 0xffff0000, v21
	v_and_b32_e32 v105, 0xffff0000, v23
	v_fma_f32 v104, v78, v70, v104
	v_fma_f32 v105, v78, v71, v105
	v_fma_f32 v104, -v79, v71, v104
	v_fma_f32 v71, v79, v70, v105
	v_mov_b32_e32 v70, v104
	v_cvt_pk_bf16_f32 v108, v64, v66
	v_cvt_pk_bf16_f32 v109, v68, v70
	v_cvt_pk_bf16_f32 v110, v65, v67
	v_cvt_pk_bf16_f32 v111, v69, v71
	global_store_dwordx2 v101, v[108:109], s[24:25] offset:512
	global_store_dwordx2 v101, v[110:111], s[24:25] offset:640
	v_lshlrev_b32_e32 v104, 16, v24
	v_lshlrev_b32_e32 v105, 16, v26
	v_fma_f32 v104, v72, v64, v104
	v_fma_f32 v105, v72, v65, v105
	v_fma_f32 v104, -v73, v65, v104
	v_fma_f32 v65, v73, v64, v105
	v_mov_b32_e32 v64, v104
	v_and_b32_e32 v104, 0xffff0000, v24
	v_and_b32_e32 v105, 0xffff0000, v26
	v_fma_f32 v104, v74, v66, v104
	v_fma_f32 v105, v74, v67, v105
	v_fma_f32 v104, -v75, v67, v104
	v_fma_f32 v67, v75, v66, v105
	v_mov_b32_e32 v66, v104
	v_lshlrev_b32_e32 v104, 16, v25
	v_lshlrev_b32_e32 v105, 16, v27
	v_fma_f32 v104, v76, v68, v104
	v_fma_f32 v105, v76, v69, v105
	v_fma_f32 v104, -v77, v69, v104
	v_fma_f32 v69, v77, v68, v105
	v_mov_b32_e32 v68, v104
	v_and_b32_e32 v104, 0xffff0000, v25
	v_and_b32_e32 v105, 0xffff0000, v27
	v_fma_f32 v104, v78, v70, v104
	v_fma_f32 v105, v78, v71, v105
	v_fma_f32 v104, -v79, v71, v104
	v_fma_f32 v71, v79, v70, v105
	v_mov_b32_e32 v70, v104
	v_cvt_pk_bf16_f32 v112, v64, v66
	v_cvt_pk_bf16_f32 v113, v68, v70
	v_cvt_pk_bf16_f32 v114, v65, v67
	v_cvt_pk_bf16_f32 v115, v69, v71
	global_store_dwordx2 v101, v[112:113], s[24:25]
	global_store_dwordx2 v101, v[114:115], s[24:25] offset:128
	v_lshlrev_b32_e32 v104, 16, v28
	v_lshlrev_b32_e32 v105, 16, v30
	v_fma_f32 v104, v72, v64, v104
	v_fma_f32 v105, v72, v65, v105
	v_fma_f32 v104, -v73, v65, v104
	v_fma_f32 v65, v73, v64, v105
	v_mov_b32_e32 v64, v104
	v_and_b32_e32 v104, 0xffff0000, v28
	v_and_b32_e32 v105, 0xffff0000, v30
	v_fma_f32 v104, v74, v66, v104
	v_fma_f32 v105, v74, v67, v105
	v_fma_f32 v104, -v75, v67, v104
	v_fma_f32 v67, v75, v66, v105
	v_mov_b32_e32 v66, v104
	v_lshlrev_b32_e32 v104, 16, v29
	v_lshlrev_b32_e32 v105, 16, v31
	v_fma_f32 v104, v76, v68, v104
	v_fma_f32 v105, v76, v69, v105
	v_fma_f32 v104, -v77, v69, v104
	v_fma_f32 v69, v77, v68, v105
	v_mov_b32_e32 v68, v104
	v_and_b32_e32 v104, 0xffff0000, v29
	v_and_b32_e32 v105, 0xffff0000, v31
	v_fma_f32 v104, v78, v70, v104
	v_fma_f32 v105, v78, v71, v105
	v_fma_f32 v104, -v79, v71, v104
	v_fma_f32 v71, v79, v70, v105
	v_mov_b32_e32 v70, v104
	v_cvt_pk_bf16_f32 v108, v64, v66
	v_cvt_pk_bf16_f32 v109, v68, v70
	v_cvt_pk_bf16_f32 v110, v65, v67
	v_cvt_pk_bf16_f32 v111, v69, v71
	global_store_dwordx2 v100, v[108:109], s[24:25] offset:3584
	global_store_dwordx2 v100, v[110:111], s[24:25] offset:3712
	v_lshlrev_b32_e32 v104, 16, v32
	v_lshlrev_b32_e32 v105, 16, v34
	v_fma_f32 v104, v72, v64, v104
	v_fma_f32 v105, v72, v65, v105
	v_fma_f32 v104, -v73, v65, v104
	v_fma_f32 v65, v73, v64, v105
	v_mov_b32_e32 v64, v104
	v_and_b32_e32 v104, 0xffff0000, v32
	v_and_b32_e32 v105, 0xffff0000, v34
	v_fma_f32 v104, v74, v66, v104
	v_fma_f32 v105, v74, v67, v105
	v_fma_f32 v104, -v75, v67, v104
	v_fma_f32 v67, v75, v66, v105
	v_mov_b32_e32 v66, v104
	v_lshlrev_b32_e32 v104, 16, v33
	v_lshlrev_b32_e32 v105, 16, v35
	v_fma_f32 v104, v76, v68, v104
	v_fma_f32 v105, v76, v69, v105
	v_fma_f32 v104, -v77, v69, v104
	v_fma_f32 v69, v77, v68, v105
	v_mov_b32_e32 v68, v104
	v_and_b32_e32 v104, 0xffff0000, v33
	v_and_b32_e32 v105, 0xffff0000, v35
	v_fma_f32 v104, v78, v70, v104
	v_fma_f32 v105, v78, v71, v105
	v_fma_f32 v104, -v79, v71, v104
	v_fma_f32 v71, v79, v70, v105
	v_mov_b32_e32 v70, v104
	v_cvt_pk_bf16_f32 v112, v64, v66
	v_cvt_pk_bf16_f32 v113, v68, v70
	v_cvt_pk_bf16_f32 v114, v65, v67
	v_cvt_pk_bf16_f32 v115, v69, v71
	global_store_dwordx2 v100, v[112:113], s[24:25] offset:3072
	global_store_dwordx2 v100, v[114:115], s[24:25] offset:3200
	v_lshlrev_b32_e32 v104, 16, v36
	v_lshlrev_b32_e32 v105, 16, v38
	v_fma_f32 v104, v72, v64, v104
	v_fma_f32 v105, v72, v65, v105
	v_fma_f32 v104, -v73, v65, v104
	v_fma_f32 v65, v73, v64, v105
	v_mov_b32_e32 v64, v104
	v_and_b32_e32 v104, 0xffff0000, v36
	v_and_b32_e32 v105, 0xffff0000, v38
	v_fma_f32 v104, v74, v66, v104
	v_fma_f32 v105, v74, v67, v105
	v_fma_f32 v104, -v75, v67, v104
	v_fma_f32 v67, v75, v66, v105
	v_mov_b32_e32 v66, v104
	v_lshlrev_b32_e32 v104, 16, v37
	v_lshlrev_b32_e32 v105, 16, v39
	v_fma_f32 v104, v76, v68, v104
	v_fma_f32 v105, v76, v69, v105
	v_fma_f32 v104, -v77, v69, v104
	v_fma_f32 v69, v77, v68, v105
	v_mov_b32_e32 v68, v104
	v_and_b32_e32 v104, 0xffff0000, v37
; __device__ __forceinline__ unsigned f2bf(float f) { unsigned u = __float_as_uint(f); return (u + 0x7fffu + ((u >> 16) & 1u)) >> 16; }
; __device__ __forceinline__ void s5_scan_bg(LAS unsigned char* lds, const S5In P, const bf16_t* F, bf16_t* XB, int b, int g, const int tid) {
;     ...
;     for (int jj = 0; jj < 4; ++jj) { const int job = wid + 8 * jj, di = job >> 4, seg = job & 15;
;         const float ar = di ? a1r[1] : a1r[0], ai = di ? a1i[1] : a1i[0]; const f32x2v x0 = XI[(di * 16 + seg) * 64 + p]; float xr = x0.x, xi = x0.y;
;         bf16_t* xg = XB + ((size_t)g * 1024 + b * 256) * 256 + di * 128 + p;
; #pragma unroll
;         for (int j = 0; j < 16; ++j) { const int c = di == 0 ? seg * 16 + j : 255 - (seg * 16 + j);
;             xg[(size_t)c * 256] = (bf16_t)f2bf(xr); xg[(size_t)c * 256 + 64] = (bf16_t)f2bf(xi);
;             const float nxr = ar * xr - ai * xi + fr[jj][j], nxi = ar * xi + ai * xr + fi[jj][j]; xr = nxr; xi = nxi; } }
	v_and_b32_e32 v105, 0xffff0000, v39
	v_fma_f32 v104, v78, v70, v104
	v_fma_f32 v105, v78, v71, v105
	v_fma_f32 v104, -v79, v71, v104
	v_fma_f32 v71, v79, v70, v105
	v_mov_b32_e32 v70, v104
	v_cvt_pk_bf16_f32 v108, v64, v66
	v_cvt_pk_bf16_f32 v109, v68, v70
	v_cvt_pk_bf16_f32 v110, v65, v67
	v_cvt_pk_bf16_f32 v111, v69, v71
	global_store_dwordx2 v100, v[108:109], s[24:25] offset:2560
	global_store_dwordx2 v100, v[110:111], s[24:25] offset:2688
	v_lshlrev_b32_e32 v104, 16, v40
	v_lshlrev_b32_e32 v105, 16, v42
	v_fma_f32 v104, v72, v64, v104
	v_fma_f32 v105, v72, v65, v105
	v_fma_f32 v104, -v73, v65, v104
	v_fma_f32 v65, v73, v64, v105
	v_mov_b32_e32 v64, v104
	v_and_b32_e32 v104, 0xffff0000, v40
	v_and_b32_e32 v105, 0xffff0000, v42
	v_fma_f32 v104, v74, v66, v104
	v_fma_f32 v105, v74, v67, v105
	v_fma_f32 v104, -v75, v67, v104
	v_fma_f32 v67, v75, v66, v105
	v_mov_b32_e32 v66, v104
	v_lshlrev_b32_e32 v104, 16, v41
	v_lshlrev_b32_e32 v105, 16, v43
	v_fma_f32 v104, v76, v68, v104
	v_fma_f32 v105, v76, v69, v105
	v_fma_f32 v104, -v77, v69, v104
	v_fma_f32 v69, v77, v68, v105
	v_mov_b32_e32 v68, v104
	v_and_b32_e32 v104, 0xffff0000, v41
	v_and_b32_e32 v105, 0xffff0000, v43
	v_fma_f32 v104, v78, v70, v104
	v_fma_f32 v105, v78, v71, v105
	v_fma_f32 v104, -v79, v71, v104
	v_fma_f32 v71, v79, v70, v105
	v_mov_b32_e32 v70, v104
	v_cvt_pk_bf16_f32 v112, v64, v66
	v_cvt_pk_bf16_f32 v113, v68, v70
	v_cvt_pk_bf16_f32 v114, v65, v67
	v_cvt_pk_bf16_f32 v115, v69, v71
	global_store_dwordx2 v100, v[112:113], s[24:25] offset:2048
	global_store_dwordx2 v100, v[114:115], s[24:25] offset:2176
	v_lshlrev_b32_e32 v104, 16, v44
	v_lshlrev_b32_e32 v105, 16, v46
	v_fma_f32 v104, v72, v64, v104
	v_fma_f32 v105, v72, v65, v105
	v_fma_f32 v104, -v73, v65, v104
	v_fma_f32 v65, v73, v64, v105
	v_mov_b32_e32 v64, v104
	v_and_b32_e32 v104, 0xffff0000, v44
	v_and_b32_e32 v105, 0xffff0000, v46
	v_fma_f32 v104, v74, v66, v104
	v_fma_f32 v105, v74, v67, v105
	v_fma_f32 v104, -v75, v67, v104
	v_fma_f32 v67, v75, v66, v105
	v_mov_b32_e32 v66, v104
	v_lshlrev_b32_e32 v104, 16, v45
	v_lshlrev_b32_e32 v105, 16, v47
	v_fma_f32 v104, v76, v68, v104
	v_fma_f32 v105, v76, v69, v105
	v_fma_f32 v104, -v77, v69, v104
	v_fma_f32 v69, v77, v68, v105
	v_mov_b32_e32 v68, v104
	v_and_b32_e32 v104, 0xffff0000, v45
	v_and_b32_e32 v105, 0xffff0000, v47
	v_fma_f32 v104, v78, v70, v104
	v_fma_f32 v105, v78, v71, v105
	v_fma_f32 v104, -v79, v71, v104
	v_fma_f32 v71, v79, v70, v105
	v_mov_b32_e32 v70, v104
	v_cvt_pk_bf16_f32 v108, v64, v66
	v_cvt_pk_bf16_f32 v109, v68, v70
	v_cvt_pk_bf16_f32 v110, v65, v67
	v_cvt_pk_bf16_f32 v111, v69, v71
	global_store_dwordx2 v100, v[108:109], s[24:25] offset:1536
	global_store_dwordx2 v100, v[110:111], s[24:25] offset:1664
	v_lshlrev_b32_e32 v104, 16, v48
	v_lshlrev_b32_e32 v105, 16, v50
	v_fma_f32 v104, v72, v64, v104
	v_fma_f32 v105, v72, v65, v105
	v_fma_f32 v104, -v73, v65, v104
	v_fma_f32 v65, v73, v64, v105
	v_mov_b32_e32 v64, v104
	v_and_b32_e32 v104, 0xffff0000, v48
	v_and_b32_e32 v105, 0xffff0000, v50
	v_fma_f32 v104, v74, v66, v104
	v_fma_f32 v105, v74, v67, v105
	v_fma_f32 v104, -v75, v67, v104
	v_fma_f32 v67, v75, v66, v105
	v_mov_b32_e32 v66, v104
	v_lshlrev_b32_e32 v104, 16, v49
	v_lshlrev_b32_e32 v105, 16, v51
	v_fma_f32 v104, v76, v68, v104
	v_fma_f32 v105, v76, v69, v105
	v_fma_f32 v104, -v77, v69, v104
	v_fma_f32 v69, v77, v68, v105
	v_mov_b32_e32 v68, v104
	v_and_b32_e32 v104, 0xffff0000, v49
	v_and_b32_e32 v105, 0xffff0000, v51
	v_fma_f32 v104, v78, v70, v104
	v_fma_f32 v105, v78, v71, v105
	v_fma_f32 v104, -v79, v71, v104
	v_fma_f32 v71, v79, v70, v105
	v_mov_b32_e32 v70, v104
	v_cvt_pk_bf16_f32 v112, v64, v66
	v_cvt_pk_bf16_f32 v113, v68, v70
	v_cvt_pk_bf16_f32 v114, v65, v67
	v_cvt_pk_bf16_f32 v115, v69, v71
	global_store_dwordx2 v100, v[112:113], s[24:25] offset:1024
	global_store_dwordx2 v100, v[114:115], s[24:25] offset:1152
	v_lshlrev_b32_e32 v104, 16, v52
	v_lshlrev_b32_e32 v105, 16, v54
	v_fma_f32 v104, v72, v64, v104
	v_fma_f32 v105, v72, v65, v105
	v_fma_f32 v104, -v73, v65, v104
	v_fma_f32 v65, v73, v64, v105
	v_mov_b32_e32 v64, v104
	v_and_b32_e32 v104, 0xffff0000, v52
	v_and_b32_e32 v105, 0xffff0000, v54
	v_fma_f32 v104, v74, v66, v104
	v_fma_f32 v105, v74, v67, v105
	v_fma_f32 v104, -v75, v67, v104
	v_fma_f32 v67, v75, v66, v105
	v_mov_b32_e32 v66, v104
	v_lshlrev_b32_e32 v104, 16, v53
	v_lshlrev_b32_e32 v105, 16, v55
	v_fma_f32 v104, v76, v68, v104
	v_fma_f32 v105, v76, v69, v105
	v_fma_f32 v104, -v77, v69, v104
	v_fma_f32 v69, v77, v68, v105
	v_mov_b32_e32 v68, v104
	v_and_b32_e32 v104, 0xffff0000, v53
	v_and_b32_e32 v105, 0xffff0000, v55
	v_fma_f32 v104, v78, v70, v104
	v_fma_f32 v105, v78, v71, v105
	v_fma_f32 v104, -v79, v71, v104
	v_fma_f32 v71, v79, v70, v105
	v_mov_b32_e32 v70, v104
	v_cvt_pk_bf16_f32 v108, v64, v66
	v_cvt_pk_bf16_f32 v109, v68, v70
	v_cvt_pk_bf16_f32 v110, v65, v67
	v_cvt_pk_bf16_f32 v111, v69, v71
	global_store_dwordx2 v100, v[108:109], s[24:25] offset:512
	global_store_dwordx2 v100, v[110:111], s[24:25] offset:640
	v_lshlrev_b32_e32 v104, 16, v56
	v_lshlrev_b32_e32 v105, 16, v58
	v_fma_f32 v104, v72, v64, v104
	v_fma_f32 v105, v72, v65, v105
	v_fma_f32 v104, -v73, v65, v104
	v_fma_f32 v65, v73, v64, v105
	v_mov_b32_e32 v64, v104
	v_and_b32_e32 v104, 0xffff0000, v56
	v_and_b32_e32 v105, 0xffff0000, v58
	v_fma_f32 v104, v74, v66, v104
	v_fma_f32 v105, v74, v67, v105
	v_fma_f32 v104, -v75, v67, v104
	v_fma_f32 v67, v75, v66, v105
	v_mov_b32_e32 v66, v104
	v_lshlrev_b32_e32 v104, 16, v57
	v_lshlrev_b32_e32 v105, 16, v59
	v_fma_f32 v104, v76, v68, v104
	v_fma_f32 v105, v76, v69, v105
	v_fma_f32 v104, -v77, v69, v104
	v_fma_f32 v69, v77, v68, v105
	v_mov_b32_e32 v68, v104
	v_and_b32_e32 v104, 0xffff0000, v57
	v_and_b32_e32 v105, 0xffff0000, v59
	v_fma_f32 v104, v78, v70, v104
	v_fma_f32 v105, v78, v71, v105
	v_fma_f32 v104, -v79, v71, v104
	v_fma_f32 v71, v79, v70, v105
	v_mov_b32_e32 v70, v104
	v_cvt_pk_bf16_f32 v112, v64, v66
	v_cvt_pk_bf16_f32 v113, v68, v70
	v_cvt_pk_bf16_f32 v114, v65, v67
	v_cvt_pk_bf16_f32 v115, v69, v71
	global_store_dwordx2 v100, v[112:113], s[24:25]
	global_store_dwordx2 v100, v[114:115], s[24:25] offset:128
	s_branch .LBB0_820
